# sample attention: three segment orders by (blockIdx>>4)%3 (d1 d4 d16 / d1 d16 d4 / d16 d4 d1) so each dilation stream is spread over the whole stage (rot3)
# baseline (speedup 1.0000x reference)
; __device__ __forceinline__ float fexp2(float x) { return __builtin_amdgcn_exp2f(x); }
; __device__ __forceinline__ void attn_sample_item(const P& p, int wi, int lane) {
;     ...
;     const int bs = wi >> 5, i = (wi >> 3) & 3, h = wi & 7;
;     const int kg = lane >> 4, li = lane & 15;
;     const int srow = bs * 4 + i;
;     const float* ACC1 = (const float*)(ws + O_ACC1); const float* rstd1 = (const float*)(ws + O_RSTD1);
;     float q[8];
;     { const float rq = rstd1[TP + srow] * (0.08838834764831845f * LOG2E);
;       const f32x4 q0 = acc1_4(ACC1, srow, 3072 + h * 128 + 8 * li), q1 = acc1_4(ACC1, srow, 3072 + h * 128 + 8 * li + 4);
;       q[0] = q0[0] * rq; q[1] = q0[1] * rq; q[2] = q0[2] * rq; q[3] = q0[3] * rq; q[4] = q1[0] * rq; q[5] = q1[1] * rq; q[6] = q1[2] * rq; q[7] = q1[3] * rq; }
;     if (kg == 0) {
;         const float rs = rstd1[TP + srow];
;         float* ko = p.out + OUT_KN + (size_t)srow * 1024 + h * 128 + 8 * li; float* vo = p.out + OUT_VN + (size_t)srow * 1024 + h * 128 + 8 * li;
;         *(f32x4*)ko = acc1_4(ACC1, srow, 4096 + h * 128 + 8 * li) * rs; *(f32x4*)(ko + 4) = acc1_4(ACC1, srow, 4096 + h * 128 + 8 * li + 4) * rs;
;         *(f32x4*)vo = acc1_4(ACC1, srow, 5120 + h * 128 + 8 * li) * rs; *(f32x4*)(vo + 4) = acc1_4(ACC1, srow, 5120 + h * 128 + 8 * li + 4) * rs;
;     }
;     float m = -1e30f, l = 0.f, acc[8];
; #pragma unroll
;     for (int e = 0; e < 8; ++e) acc[e] = 0.f;
;     const float sl = fexp2(-(float)(h + 1)) * LOG2E;
;     for (int g = 0; g < 3; ++g) {
;         const int d = 1 << (2 * g);
; #pragma unroll 3
;         for (int jj = 0; jj < 33; ++jj) {
;             const int j = 4 * jj + kg; const bool valid = j <= 128; const int jc = valid ? j : 128;
;             const int idx = 2048 + i - d * jc;
;             f32x4 k0, k1, v0, v1;
;             if (idx < 2048) { const size_t off = (((size_t)bs * 2048 + idx) * 8 + h) * 128 + 8 * li;
;                 k0 = __builtin_nontemporal_load((const f32x4*)(p.cache_k + off)); k1 = __builtin_nontemporal_load((const f32x4*)(p.cache_k + off + 4)); v0 = __builtin_nontemporal_load((const f32x4*)(p.cache_v + off)); v1 = __builtin_nontemporal_load((const f32x4*)(p.cache_v + off + 4)); }
;             else { const int nr = bs * 4 + (idx - 2048); const float rsn = rstd1[TP + nr]; const int c0 = 4096 + h * 128 + 8 * li;
.Las_item:
	s_ashr_i32 s14, s3, 5
	s_bfe_u32 s15, s3, 0x20003
	s_and_b32 s16, s3, 7
	s_lshl_b32 s17, s14, 2
	s_or_b32 s17, s17, s15
	s_lshl_b32 s18, s14, 23
	s_add_u32 s20, s56, s18
	s_addc_u32 s21, s57, 0
	s_add_u32 s24, s58, s18
	s_addc_u32 s25, s59, 0
	s_lshl_b32 s18, s17, 2
	s_add_u32 s18, s18, 0x8000
	s_load_dword s19, s[10:11], s18
	s_lshl_b32 s23, s16, 9
	v_and_b32_e32 v72, 15, v230
	v_lshlrev_b32_e32 v72, 4, v72
	v_bfe_u32 v73, v230, 4, 2
	v_cvt_f32_u32_e32 v202, v73
	v_add_u32_e32 v72, s23, v72
	s_add_u32 s43, s15, 0x800
	s_lshl_b32 s43, s43, 12
	v_add_u32_e32 v203, s43, v72
	s_sub_u32 s43, 0x7a, s16
	s_lshl_b32 s43, s43, 23
	v_mov_b32_e32 v201, s43
	v_mul_f32_e32 v201, 0xbfb8aa3b, v201
	s_mul_i32 s43, s17, 0x6000
	s_add_u32 s43, s43, 0x3000
	v_add_u32_e32 v64, s43, v72
	v_sub_u32_e32 v67, s15, v73
	v_max_i32_e32 v67, 0, v67
	v_lshl_add_u32 v67, s14, 2, v67
	v_lshlrev_b32_e32 v66, 2, v67
	v_add_u32_e32 v66, 0x8000, v66
	v_mul_u32_u24_e32 v65, 0x6000, v67
	v_add_u32_e32 v65, 0x4000, v65
	v_add_u32_e32 v65, v65, v72
	v_lshlrev_b32_e32 v68, 12, v73
	v_sub_u32_e32 v68, v203, v68
	s_mov_b32 s43, 0x7ff000
	v_add_u32_e32 v69, s43, v72
	v_min_u32_e32 v68, v68, v69
	v_add_u32_e32 v69, 0xfff80000, v203
	global_load_dword v70, v66, s[10:11]
	global_load_dwordx4 v[128:131], v68, s[20:21]
	global_load_dwordx4 v[132:135], v68, s[20:21] offset:256
	global_load_dwordx4 v[136:139], v68, s[24:25]
	global_load_dwordx4 v[140:143], v68, s[24:25] offset:256
	global_load_dwordx4 v[144:147], v69, s[20:21]
	global_load_dwordx4 v[148:151], v69, s[20:21] offset:256
	global_load_dwordx4 v[152:155], v69, s[24:25]
	global_load_dwordx4 v[156:159], v69, s[24:25] offset:256
	v_mov_b32_e32 v71, v64
	global_load_dwordx4 v[0:3], v71, s[8:9]
	v_add_u32_e32 v71, 0x300000, v71
	global_load_dwordx4 v[4:7], v71, s[8:9]
	v_add_u32_e32 v71, 0x300000, v71
	global_load_dwordx4 v[8:11], v71, s[8:9]
	v_add_u32_e32 v71, 0x300000, v71
	global_load_dwordx4 v[12:15], v71, s[8:9]
	v_add_u32_e32 v71, 0x300000, v71
	global_load_dwordx4 v[16:19], v71, s[8:9]
	v_add_u32_e32 v71, 0x300000, v71
	global_load_dwordx4 v[20:23], v71, s[8:9]
	v_add_u32_e32 v71, 0x300000, v71
	global_load_dwordx4 v[24:27], v71, s[8:9]
	v_add_u32_e32 v71, 0x300000, v71
	global_load_dwordx4 v[28:31], v71, s[8:9]
	v_mov_b32_e32 v71, v64
	global_load_dwordx4 v[32:35], v71, s[8:9] offset:256
	v_add_u32_e32 v71, 0x300000, v71
	global_load_dwordx4 v[36:39], v71, s[8:9] offset:256
	v_add_u32_e32 v71, 0x300000, v71
	global_load_dwordx4 v[40:43], v71, s[8:9] offset:256
	v_add_u32_e32 v71, 0x300000, v71
	global_load_dwordx4 v[44:47], v71, s[8:9] offset:256
	v_add_u32_e32 v71, 0x300000, v71
	global_load_dwordx4 v[48:51], v71, s[8:9] offset:256
	v_add_u32_e32 v71, 0x300000, v71
	global_load_dwordx4 v[52:55], v71, s[8:9] offset:256
	v_add_u32_e32 v71, 0x300000, v71
	global_load_dwordx4 v[56:59], v71, s[8:9] offset:256
	v_add_u32_e32 v71, 0x300000, v71
	global_load_dwordx4 v[60:63], v71, s[8:9] offset:256
	s_waitcnt vmcnt(8)
	v_add_f32_e32 v160, v0, v4
	v_add_f32_e32 v161, v1, v5
	v_add_f32_e32 v162, v2, v6
	v_add_f32_e32 v163, v3, v7
	v_add_f32_e32 v160, v160, v8
	v_add_f32_e32 v161, v161, v9
	v_add_f32_e32 v162, v162, v10
	v_add_f32_e32 v163, v163, v11
	v_add_f32_e32 v160, v160, v12
	v_add_f32_e32 v161, v161, v13
	v_add_f32_e32 v162, v162, v14
	v_add_f32_e32 v163, v163, v15
	v_add_f32_e32 v160, v160, v16
	v_add_f32_e32 v161, v161, v17
	v_add_f32_e32 v162, v162, v18
	v_add_f32_e32 v163, v163, v19
	v_add_f32_e32 v160, v160, v20
	v_add_f32_e32 v161, v161, v21
	v_add_f32_e32 v162, v162, v22
	v_add_f32_e32 v163, v163, v23
	v_add_f32_e32 v160, v160, v24
	v_add_f32_e32 v161, v161, v25
	v_add_f32_e32 v162, v162, v26
	v_add_f32_e32 v163, v163, v27
	v_add_f32_e32 v160, v160, v28
	v_add_f32_e32 v161, v161, v29
	v_add_f32_e32 v162, v162, v30
	v_add_f32_e32 v163, v163, v31
	v_mov_b32_e32 v71, v65
	global_load_dwordx4 v[0:3], v71, s[8:9]
	v_add_u32_e32 v71, 0x300000, v71
	global_load_dwordx4 v[4:7], v71, s[8:9]
	v_add_u32_e32 v71, 0x300000, v71
	global_load_dwordx4 v[8:11], v71, s[8:9]
	v_add_u32_e32 v71, 0x300000, v71
	global_load_dwordx4 v[12:15], v71, s[8:9]
	v_add_u32_e32 v71, 0x300000, v71
	global_load_dwordx4 v[16:19], v71, s[8:9]
	v_add_u32_e32 v71, 0x300000, v71
	global_load_dwordx4 v[20:23], v71, s[8:9]
	v_add_u32_e32 v71, 0x300000, v71
	global_load_dwordx4 v[24:27], v71, s[8:9]
	v_add_u32_e32 v71, 0x300000, v71
	global_load_dwordx4 v[28:31], v71, s[8:9]
	s_waitcnt vmcnt(8)
	v_add_f32_e32 v164, v32, v36
	v_add_f32_e32 v165, v33, v37
	v_add_f32_e32 v166, v34, v38
	v_add_f32_e32 v167, v35, v39
	v_add_f32_e32 v164, v164, v40
	v_add_f32_e32 v165, v165, v41
	v_add_f32_e32 v166, v166, v42
	v_add_f32_e32 v167, v167, v43
	v_add_f32_e32 v164, v164, v44
	v_add_f32_e32 v165, v165, v45
	v_add_f32_e32 v166, v166, v46
	v_add_f32_e32 v167, v167, v47
	v_add_f32_e32 v164, v164, v48
	v_add_f32_e32 v165, v165, v49
	v_add_f32_e32 v166, v166, v50
	v_add_f32_e32 v167, v167, v51
	v_add_f32_e32 v164, v164, v52
	v_add_f32_e32 v165, v165, v53
	v_add_f32_e32 v166, v166, v54
	v_add_f32_e32 v167, v167, v55
	v_add_f32_e32 v164, v164, v56
	v_add_f32_e32 v165, v165, v57
	v_add_f32_e32 v166, v166, v58
	v_add_f32_e32 v167, v167, v59
	v_add_f32_e32 v164, v164, v60
	v_add_f32_e32 v165, v165, v61
	v_add_f32_e32 v166, v166, v62
	v_add_f32_e32 v167, v167, v63
	v_mov_b32_e32 v71, v65
	global_load_dwordx4 v[32:35], v71, s[8:9] offset:256
	v_add_u32_e32 v71, 0x300000, v71
	global_load_dwordx4 v[36:39], v71, s[8:9] offset:256
	v_add_u32_e32 v71, 0x300000, v71
	global_load_dwordx4 v[40:43], v71, s[8:9] offset:256
	v_add_u32_e32 v71, 0x300000, v71
	global_load_dwordx4 v[44:47], v71, s[8:9] offset:256
	v_add_u32_e32 v71, 0x300000, v71
	global_load_dwordx4 v[48:51], v71, s[8:9] offset:256
	v_add_u32_e32 v71, 0x300000, v71
	global_load_dwordx4 v[52:55], v71, s[8:9] offset:256
	v_add_u32_e32 v71, 0x300000, v71
	global_load_dwordx4 v[56:59], v71, s[8:9] offset:256
	v_add_u32_e32 v71, 0x300000, v71
	global_load_dwordx4 v[60:63], v71, s[8:9] offset:256
	s_waitcnt vmcnt(8)
; __device__ __forceinline__ f32x4 acc1_4(const float* ACC1, int srow, int col) {
;     f32x4 s = *(const f32x4*)(ACC1 + (size_t)srow * N1 + col);
; #pragma unroll
;     for (int kp = 1; kp < 8; ++kp) s += *(const f32x4*)(ACC1 + ((size_t)kp * TS + srow) * N1 + col);
;     return s;
; __device__ __forceinline__ void attn_sample_item(const P& p, int wi, int lane) {
;     ...
;         const float rs = rstd1[TP + srow];
;         float* ko = p.out + OUT_KN + (size_t)srow * 1024 + h * 128 + 8 * li; float* vo = p.out + OUT_VN + (size_t)srow * 1024 + h * 128 + 8 * li;
;         *(f32x4*)ko = acc1_4(ACC1, srow, 4096 + h * 128 + 8 * li) * rs; *(f32x4*)(ko + 4) = acc1_4(ACC1, srow, 4096 + h * 128 + 8 * li + 4) * rs;
;         *(f32x4*)vo = acc1_4(ACC1, srow, 5120 + h * 128 + 8 * li) * rs; *(f32x4*)(vo + 4) = acc1_4(ACC1, srow, 5120 + h * 128 + 8 * li + 4) * rs;
	v_add_f32_e32 v176, v0, v4
	v_add_f32_e32 v177, v1, v5
	v_add_f32_e32 v178, v2, v6
	v_add_f32_e32 v179, v3, v7
	v_add_f32_e32 v176, v176, v8
	v_add_f32_e32 v177, v177, v9
	v_add_f32_e32 v178, v178, v10
	v_add_f32_e32 v179, v179, v11
	v_add_f32_e32 v176, v176, v12
	v_add_f32_e32 v177, v177, v13
	v_add_f32_e32 v178, v178, v14
	v_add_f32_e32 v179, v179, v15
	v_add_f32_e32 v176, v176, v16
	v_add_f32_e32 v177, v177, v17
	v_add_f32_e32 v178, v178, v18
	v_add_f32_e32 v179, v179, v19
	v_add_f32_e32 v176, v176, v20
	v_add_f32_e32 v177, v177, v21
	v_add_f32_e32 v178, v178, v22
	v_add_f32_e32 v179, v179, v23
	v_add_f32_e32 v176, v176, v24
	v_add_f32_e32 v177, v177, v25
	v_add_f32_e32 v178, v178, v26
	v_add_f32_e32 v179, v179, v27
	v_add_f32_e32 v176, v176, v28
	v_add_f32_e32 v177, v177, v29
	v_add_f32_e32 v178, v178, v30
	v_add_f32_e32 v179, v179, v31
	v_add_u32_e32 v71, 0x1000, v65
	global_load_dwordx4 v[0:3], v71, s[8:9]
	v_add_u32_e32 v71, 0x300000, v71
	global_load_dwordx4 v[4:7], v71, s[8:9]
	v_add_u32_e32 v71, 0x300000, v71
	global_load_dwordx4 v[8:11], v71, s[8:9]
	v_add_u32_e32 v71, 0x300000, v71
	global_load_dwordx4 v[12:15], v71, s[8:9]
	v_add_u32_e32 v71, 0x300000, v71
	global_load_dwordx4 v[16:19], v71, s[8:9]
	v_add_u32_e32 v71, 0x300000, v71
	global_load_dwordx4 v[20:23], v71, s[8:9]
	v_add_u32_e32 v71, 0x300000, v71
	global_load_dwordx4 v[24:27], v71, s[8:9]
	v_add_u32_e32 v71, 0x300000, v71
	global_load_dwordx4 v[28:31], v71, s[8:9]
	s_waitcnt vmcnt(8)
	v_add_f32_e32 v180, v32, v36
	v_add_f32_e32 v181, v33, v37
	v_add_f32_e32 v182, v34, v38
	v_add_f32_e32 v183, v35, v39
	v_add_f32_e32 v180, v180, v40
	v_add_f32_e32 v181, v181, v41
	v_add_f32_e32 v182, v182, v42
	v_add_f32_e32 v183, v183, v43
	v_add_f32_e32 v180, v180, v44
	v_add_f32_e32 v181, v181, v45
	v_add_f32_e32 v182, v182, v46
	v_add_f32_e32 v183, v183, v47
	v_add_f32_e32 v180, v180, v48
	v_add_f32_e32 v181, v181, v49
	v_add_f32_e32 v182, v182, v50
	v_add_f32_e32 v183, v183, v51
	v_add_f32_e32 v180, v180, v52
	v_add_f32_e32 v181, v181, v53
	v_add_f32_e32 v182, v182, v54
	v_add_f32_e32 v183, v183, v55
	v_add_f32_e32 v180, v180, v56
	v_add_f32_e32 v181, v181, v57
	v_add_f32_e32 v182, v182, v58
	v_add_f32_e32 v183, v183, v59
	v_add_f32_e32 v180, v180, v60
	v_add_f32_e32 v181, v181, v61
	v_add_f32_e32 v182, v182, v62
	v_add_f32_e32 v183, v183, v63
	v_add_u32_e32 v71, 0x1000, v65
	global_load_dwordx4 v[32:35], v71, s[8:9] offset:256
	v_add_u32_e32 v71, 0x300000, v71
	global_load_dwordx4 v[36:39], v71, s[8:9] offset:256
	v_add_u32_e32 v71, 0x300000, v71
	global_load_dwordx4 v[40:43], v71, s[8:9] offset:256
	v_add_u32_e32 v71, 0x300000, v71
	global_load_dwordx4 v[44:47], v71, s[8:9] offset:256
	v_add_u32_e32 v71, 0x300000, v71
	global_load_dwordx4 v[48:51], v71, s[8:9] offset:256
	v_add_u32_e32 v71, 0x300000, v71
	global_load_dwordx4 v[52:55], v71, s[8:9] offset:256
	v_add_u32_e32 v71, 0x300000, v71
	global_load_dwordx4 v[56:59], v71, s[8:9] offset:256
	v_add_u32_e32 v71, 0x300000, v71
	global_load_dwordx4 v[60:63], v71, s[8:9] offset:256
	s_waitcnt vmcnt(8)
	v_add_f32_e32 v184, v0, v4
	v_add_f32_e32 v185, v1, v5
	v_add_f32_e32 v186, v2, v6
	v_add_f32_e32 v187, v3, v7
	v_add_f32_e32 v184, v184, v8
	v_add_f32_e32 v185, v185, v9
	v_add_f32_e32 v186, v186, v10
	v_add_f32_e32 v187, v187, v11
	v_add_f32_e32 v184, v184, v12
	v_add_f32_e32 v185, v185, v13
	v_add_f32_e32 v186, v186, v14
	v_add_f32_e32 v187, v187, v15
	v_add_f32_e32 v184, v184, v16
	v_add_f32_e32 v185, v185, v17
	v_add_f32_e32 v186, v186, v18
	v_add_f32_e32 v187, v187, v19
	v_add_f32_e32 v184, v184, v20
	v_add_f32_e32 v185, v185, v21
	v_add_f32_e32 v186, v186, v22
	v_add_f32_e32 v187, v187, v23
	v_add_f32_e32 v184, v184, v24
	v_add_f32_e32 v185, v185, v25
	v_add_f32_e32 v186, v186, v26
	v_add_f32_e32 v187, v187, v27
	v_add_f32_e32 v184, v184, v28
	v_add_f32_e32 v185, v185, v29
	v_add_f32_e32 v186, v186, v30
	v_add_f32_e32 v187, v187, v31
	s_waitcnt vmcnt(0)
	v_add_f32_e32 v188, v32, v36
	v_add_f32_e32 v189, v33, v37
	v_add_f32_e32 v190, v34, v38
	v_add_f32_e32 v191, v35, v39
	v_add_f32_e32 v188, v188, v40
	v_add_f32_e32 v189, v189, v41
	v_add_f32_e32 v190, v190, v42
	v_add_f32_e32 v191, v191, v43
	v_add_f32_e32 v188, v188, v44
	v_add_f32_e32 v189, v189, v45
	v_add_f32_e32 v190, v190, v46
	v_add_f32_e32 v191, v191, v47
	v_add_f32_e32 v188, v188, v48
	v_add_f32_e32 v189, v189, v49
	v_add_f32_e32 v190, v190, v50
	v_add_f32_e32 v191, v191, v51
	v_add_f32_e32 v188, v188, v52
	v_add_f32_e32 v189, v189, v53
	v_add_f32_e32 v190, v190, v54
	v_add_f32_e32 v191, v191, v55
	v_add_f32_e32 v188, v188, v56
	v_add_f32_e32 v189, v189, v57
	v_add_f32_e32 v190, v190, v58
	v_add_f32_e32 v191, v191, v59
	v_add_f32_e32 v188, v188, v60
	v_add_f32_e32 v189, v189, v61
	v_add_f32_e32 v190, v190, v62
	v_add_f32_e32 v191, v191, v63
	s_waitcnt lgkmcnt(0)
; __device__ __forceinline__ float fexp2(float x) { return __builtin_amdgcn_exp2f(x); }
; __device__ __forceinline__ void attn_sample_item(const P& p, int wi, int lane) {
;     ...
;     { const float rq = rstd1[TP + srow] * (0.08838834764831845f * LOG2E);
;       const f32x4 q0 = acc1_4(ACC1, srow, 3072 + h * 128 + 8 * li), q1 = acc1_4(ACC1, srow, 3072 + h * 128 + 8 * li + 4);
;       q[0] = q0[0] * rq; q[1] = q0[1] * rq; q[2] = q0[2] * rq; q[3] = q0[3] * rq; q[4] = q1[0] * rq; q[5] = q1[1] * rq; q[6] = q1[2] * rq; q[7] = q1[3] * rq; }
;     if (kg == 0) {
;         const float rs = rstd1[TP + srow];
;         float* ko = p.out + OUT_KN + (size_t)srow * 1024 + h * 128 + 8 * li; float* vo = p.out + OUT_VN + (size_t)srow * 1024 + h * 128 + 8 * li;
;         *(f32x4*)ko = acc1_4(ACC1, srow, 4096 + h * 128 + 8 * li) * rs; *(f32x4*)(ko + 4) = acc1_4(ACC1, srow, 4096 + h * 128 + 8 * li + 4) * rs;
;         *(f32x4*)vo = acc1_4(ACC1, srow, 5120 + h * 128 + 8 * li) * rs; *(f32x4*)(vo + 4) = acc1_4(ACC1, srow, 5120 + h * 128 + 8 * li + 4) * rs;
;     }
;     float m = -1e30f, l = 0.f, acc[8];
; #pragma unroll
;     for (int e = 0; e < 8; ++e) acc[e] = 0.f;
;     const float sl = fexp2(-(float)(h + 1)) * LOG2E;
;     for (int g = 0; g < 3; ++g) {
;         const int d = 1 << (2 * g);
; #pragma unroll 3
;         for (int jj = 0; jj < 33; ++jj) {
;             const int j = 4 * jj + kg; const bool valid = j <= 128; const int jc = valid ? j : 128;
;             const int idx = 2048 + i - d * jc;
;             f32x4 k0, k1, v0, v1;
;             if (idx < 2048) { const size_t off = (((size_t)bs * 2048 + idx) * 8 + h) * 128 + 8 * li;
;                 k0 = __builtin_nontemporal_load((const f32x4*)(p.cache_k + off)); k1 = __builtin_nontemporal_load((const f32x4*)(p.cache_k + off + 4)); v0 = __builtin_nontemporal_load((const f32x4*)(p.cache_v + off)); v1 = __builtin_nontemporal_load((const f32x4*)(p.cache_v + off + 4)); }
;             else { const int nr = bs * 4 + (idx - 2048); const float rsn = rstd1[TP + nr]; const int c0 = 4096 + h * 128 + 8 * li;
;                 k0 = acc1_4(ACC1, nr, c0) * rsn; k1 = acc1_4(ACC1, nr, c0 + 4) * rsn; v0 = acc1_4(ACC1, nr, c0 + 1024) * rsn; v1 = acc1_4(ACC1, nr, c0 + 1028) * rsn; }
	v_mov_b32_e32 v71, s19
	v_mul_f32_e32 v71, 0x3e0293ee, v71
	v_mul_f32_e32 v160, v160, v71
	v_mul_f32_e32 v161, v161, v71
	v_mul_f32_e32 v162, v162, v71
	v_mul_f32_e32 v163, v163, v71
	v_mul_f32_e32 v164, v164, v71
	v_mul_f32_e32 v165, v165, v71
	v_mul_f32_e32 v166, v166, v71
	v_mul_f32_e32 v167, v167, v71
	v_mul_f32_e32 v176, v176, v70
	v_mul_f32_e32 v177, v177, v70
	v_mul_f32_e32 v178, v178, v70
	v_mul_f32_e32 v179, v179, v70
	v_mul_f32_e32 v180, v180, v70
	v_mul_f32_e32 v181, v181, v70
	v_mul_f32_e32 v182, v182, v70
	v_mul_f32_e32 v183, v183, v70
	v_mul_f32_e32 v184, v184, v70
	v_mul_f32_e32 v185, v185, v70
	v_mul_f32_e32 v186, v186, v70
	v_mul_f32_e32 v187, v187, v70
	v_mul_f32_e32 v188, v188, v70
	v_mul_f32_e32 v189, v189, v70
	v_mul_f32_e32 v190, v190, v70
	v_mul_f32_e32 v191, v191, v70
	s_lshl_b32 s43, s17, 12
	v_add_u32_e32 v71, s43, v72
	s_mov_b64 exec, 0xffff
	global_store_dwordx4 v71, v[176:179], s[26:27]
	global_store_dwordx4 v71, v[180:183], s[26:27] offset:256
	global_store_dwordx4 v71, v[184:187], s[28:29]
	global_store_dwordx4 v71, v[188:191], s[28:29] offset:256
	s_mov_b64 exec, -1
	v_cmp_ge_u32_e32 vcc, s15, v73
	s_nop 1
	v_cndmask_b32_e32 v128, v128, v176, vcc
	v_cndmask_b32_e32 v129, v129, v177, vcc
	v_cndmask_b32_e32 v130, v130, v178, vcc
	v_cndmask_b32_e32 v131, v131, v179, vcc
	v_cndmask_b32_e32 v132, v132, v180, vcc
	v_cndmask_b32_e32 v133, v133, v181, vcc
	v_cndmask_b32_e32 v134, v134, v182, vcc
	v_cndmask_b32_e32 v135, v135, v183, vcc
	v_cndmask_b32_e32 v136, v136, v184, vcc
	v_cndmask_b32_e32 v137, v137, v185, vcc
	v_cndmask_b32_e32 v138, v138, v186, vcc
	v_cndmask_b32_e32 v139, v139, v187, vcc
	v_cndmask_b32_e32 v140, v140, v188, vcc
	v_cndmask_b32_e32 v141, v141, v189, vcc
	v_cndmask_b32_e32 v142, v142, v190, vcc
	v_cndmask_b32_e32 v143, v143, v191, vcc
	v_bfe_u32 v183, v230, 4, 2
	s_lshr_b32 s43, s2, 4
	s_mul_i32 s42, s43, 11
	s_lshr_b32 s42, s42, 5
	s_mul_i32 s42, s42, 3
	s_sub_u32 s43, s43, s42
	v_lshlrev_b32_e32 v176, 14, v183
	v_sub_u32_e32 v176, v203, v176
	v_add_u32_e32 v176, 0xc000, v176
	v_lshlrev_b32_e32 v177, 16, v183
	v_sub_u32_e32 v177, v203, v177
	v_add_u32_e32 v177, 0x30000, v177
	v_add_f32_e32 v182, 1.0, v202
	v_mul_f32_e32 v182, v182, v201
	v_mul_f32_e32 v178, 4.0, v182
	v_mul_f32_e32 v179, 16.0, v182
	v_mul_f32_e32 v180, 16.0, v201
	v_mul_f32_e32 v181, 64.0, v201
	v_mul_f32_e32 v196, 4.0, v201
	s_cmp_eq_u32 s43, 1
	s_cbranch_scc0 .Las_noswap
	v_swap_b32 v176, v177
	v_swap_b32 v178, v179
	v_swap_b32 v180, v181
.Las_noswap:
	s_cmp_eq_u32 s43, 2
	s_cbranch_scc1 .Las_fillR
	v_lshlrev_b32_e32 v195, 12, v183
	v_sub_u32_e32 v195, v203, v195
	s_mov_b32 s42, 0xffffc000
	v_add_u32_e32 v195, s42, v195
	global_load_dwordx4 v[16:19], v195, s[20:21]
	global_load_dwordx4 v[20:23], v195, s[20:21] offset:256
	global_load_dwordx4 v[24:27], v195, s[24:25]
	global_load_dwordx4 v[28:31], v195, s[24:25] offset:256
	v_add_u32_e32 v195, s42, v195
	global_load_dwordx4 v[32:35], v195, s[20:21]
	global_load_dwordx4 v[36:39], v195, s[20:21] offset:256
	global_load_dwordx4 v[40:43], v195, s[24:25]
	global_load_dwordx4 v[44:47], v195, s[24:25] offset:256
	v_add_u32_e32 v195, s42, v195
	global_load_dwordx4 v[48:51], v195, s[20:21]
	global_load_dwordx4 v[52:55], v195, s[20:21] offset:256
	global_load_dwordx4 v[56:59], v195, s[24:25]
	global_load_dwordx4 v[60:63], v195, s[24:25] offset:256
	v_add_u32_e32 v195, s42, v195
	global_load_dwordx4 v[64:67], v195, s[20:21]
	global_load_dwordx4 v[68:71], v195, s[20:21] offset:256
	global_load_dwordx4 v[72:75], v195, s[24:25]
	global_load_dwordx4 v[76:79], v195, s[24:25] offset:256
	v_add_u32_e32 v195, s42, v195
	global_load_dwordx4 v[80:83], v195, s[20:21]
	global_load_dwordx4 v[84:87], v195, s[20:21] offset:256
	global_load_dwordx4 v[88:91], v195, s[24:25]
	global_load_dwordx4 v[92:95], v195, s[24:25] offset:256
	v_add_u32_e32 v195, s42, v195
	global_load_dwordx4 v[96:99], v195, s[20:21]
	global_load_dwordx4 v[100:103], v195, s[20:21] offset:256
	global_load_dwordx4 v[104:107], v195, s[24:25]
	global_load_dwordx4 v[108:111], v195, s[24:25] offset:256
	v_add_u32_e32 v195, s42, v195
	global_load_dwordx4 v[112:115], v195, s[20:21]
	global_load_dwordx4 v[116:119], v195, s[20:21] offset:256
	global_load_dwordx4 v[120:123], v195, s[24:25]
	global_load_dwordx4 v[124:127], v195, s[24:25] offset:256
	v_add_u32_e32 v195, s42, v195
	global_load_dwordx4 v[0:3], v195, s[20:21]
	global_load_dwordx4 v[4:7], v195, s[20:21] offset:256
	global_load_dwordx4 v[8:11], v195, s[24:25]
	global_load_dwordx4 v[12:15], v195, s[24:25] offset:256
	s_branch .Las_filled
; __device__ __forceinline__ float fexp2(float x) { return __builtin_amdgcn_exp2f(x); }
; __device__ __forceinline__ void attn_sample_item(const P& p, int wi, int lane) {
;     ...
;     for (int g = 0; g < 3; ++g) {
;         const int d = 1 << (2 * g);
; #pragma unroll 3
;         for (int jj = 0; jj < 33; ++jj) {
;             const int j = 4 * jj + kg; const bool valid = j <= 128; const int jc = valid ? j : 128;
;             const int idx = 2048 + i - d * jc;
;             f32x4 k0, k1, v0, v1;
;             if (idx < 2048) { const size_t off = (((size_t)bs * 2048 + idx) * 8 + h) * 128 + 8 * li;
;                 k0 = __builtin_nontemporal_load((const f32x4*)(p.cache_k + off)); k1 = __builtin_nontemporal_load((const f32x4*)(p.cache_k + off + 4)); v0 = __builtin_nontemporal_load((const f32x4*)(p.cache_v + off)); v1 = __builtin_nontemporal_load((const f32x4*)(p.cache_v + off + 4)); }
;             else { const int nr = bs * 4 + (idx - 2048); const float rsn = rstd1[TP + nr]; const int c0 = 4096 + h * 128 + 8 * li;
;                 k0 = acc1_4(ACC1, nr, c0) * rsn; k1 = acc1_4(ACC1, nr, c0 + 4) * rsn; v0 = acc1_4(ACC1, nr, c0 + 1024) * rsn; v1 = acc1_4(ACC1, nr, c0 + 1028) * rsn; }
;             float dot = (q[0] * k0[0] + q[1] * k0[1]) + (q[2] * k0[2] + q[3] * k0[3]) + (q[4] * k1[0] + q[5] * k1[1]) + (q[6] * k1[2] + q[7] * k1[3]);
;             dot += __shfl_xor(dot, 1); dot += __shfl_xor(dot, 2); dot += __shfl_xor(dot, 4); dot += __shfl_xor(dot, 8);
;             const float s = valid ? dot - sl * (float)(d * j) : -INFINITY;
;             const float mn = fmaxf(m, s), sc = fexp2(m - mn), pe = fexp2(s - mn);
;             l = l * sc + pe;
;             acc[0] = acc[0] * sc + pe * v0[0]; acc[1] = acc[1] * sc + pe * v0[1]; acc[2] = acc[2] * sc + pe * v0[2]; acc[3] = acc[3] * sc + pe * v0[3];
;             acc[4] = acc[4] * sc + pe * v1[0]; acc[5] = acc[5] * sc + pe * v1[1]; acc[6] = acc[6] * sc + pe * v1[2]; acc[7] = acc[7] * sc + pe * v1[3];
;             m = mn;
;         }
.Las_fillR:
	v_mov_b32_e32 v195, v177
	s_mov_b32 s42, 0xfffc0000
	v_add_u32_e32 v195, s42, v195
	global_load_dwordx4 v[0:3], v195, s[20:21] nt
	global_load_dwordx4 v[4:7], v195, s[20:21] offset:256 nt
	global_load_dwordx4 v[8:11], v195, s[24:25] nt
	global_load_dwordx4 v[12:15], v195, s[24:25] offset:256 nt
	v_add_u32_e32 v195, s42, v195
	global_load_dwordx4 v[16:19], v195, s[20:21] nt
	global_load_dwordx4 v[20:23], v195, s[20:21] offset:256 nt
	global_load_dwordx4 v[24:27], v195, s[24:25] nt
	global_load_dwordx4 v[28:31], v195, s[24:25] offset:256 nt
	v_add_u32_e32 v195, s42, v195
	global_load_dwordx4 v[32:35], v195, s[20:21] nt
	global_load_dwordx4 v[36:39], v195, s[20:21] offset:256 nt
	global_load_dwordx4 v[40:43], v195, s[24:25] nt
	global_load_dwordx4 v[44:47], v195, s[24:25] offset:256 nt
	v_add_u32_e32 v195, s42, v195
	global_load_dwordx4 v[48:51], v195, s[20:21] nt
	global_load_dwordx4 v[52:55], v195, s[20:21] offset:256 nt
	global_load_dwordx4 v[56:59], v195, s[24:25] nt
	global_load_dwordx4 v[60:63], v195, s[24:25] offset:256 nt
	v_add_u32_e32 v195, s42, v195
	global_load_dwordx4 v[64:67], v195, s[20:21] nt
	global_load_dwordx4 v[68:71], v195, s[20:21] offset:256 nt
	global_load_dwordx4 v[72:75], v195, s[24:25] nt
	global_load_dwordx4 v[76:79], v195, s[24:25] offset:256 nt
	v_add_u32_e32 v195, s42, v195
	global_load_dwordx4 v[80:83], v195, s[20:21] nt
	global_load_dwordx4 v[84:87], v195, s[20:21] offset:256 nt
	global_load_dwordx4 v[88:91], v195, s[24:25] nt
	global_load_dwordx4 v[92:95], v195, s[24:25] offset:256 nt
	v_add_u32_e32 v195, s42, v195
	global_load_dwordx4 v[96:99], v195, s[20:21] nt
	global_load_dwordx4 v[100:103], v195, s[20:21] offset:256 nt
	global_load_dwordx4 v[104:107], v195, s[24:25] nt
	global_load_dwordx4 v[108:111], v195, s[24:25] offset:256 nt
	v_add_u32_e32 v195, s42, v195
	global_load_dwordx4 v[112:115], v195, s[20:21] nt
	global_load_dwordx4 v[116:119], v195, s[20:21] offset:256 nt
	global_load_dwordx4 v[120:123], v195, s[24:25] nt
	global_load_dwordx4 v[124:127], v195, s[24:25] offset:256 nt
.Las_filled:
	v_mov_b32_e32 v192, 0xf149f2ca
	v_mov_b32_e32 v193, 0
	v_mov_b32_e32 v168, 0
	v_mov_b32_e32 v169, 0
	v_mov_b32_e32 v170, 0
	v_mov_b32_e32 v171, 0
	v_mov_b32_e32 v172, 0
	v_mov_b32_e32 v173, 0
	v_mov_b32_e32 v174, 0
	v_mov_b32_e32 v175, 0
	v_mul_f32_e32 v194, v201, v202
	v_mov_b32_e32 v182, 0x3dcae00d
	v_cmp_eq_u32_e32 vcc, 0, v183
	s_nop 1
	v_cndmask_b32_e32 v194, v194, v182, vcc
	v_fma_f32 v197, v160, v128, v194
	v_fmac_f32_e32 v197, v161, v129
	v_fmac_f32_e32 v197, v162, v130
	v_fmac_f32_e32 v197, v163, v131
	v_fmac_f32_e32 v197, v164, v132
	v_fmac_f32_e32 v197, v165, v133
	v_fmac_f32_e32 v197, v166, v134
	v_fmac_f32_e32 v197, v167, v135
	s_nop 1
	v_add_f32_dpp v197, v197, v197 row_ror:8 row_mask:0xf bank_mask:0xf
	s_nop 1
	v_add_f32_dpp v197, v197, v197 row_ror:4 row_mask:0xf bank_mask:0xf
	s_nop 1
	v_add_f32_dpp v197, v197, v197 row_ror:2 row_mask:0xf bank_mask:0xf
	s_nop 1
	v_add_f32_dpp v197, v197, v197 row_ror:1 row_mask:0xf bank_mask:0xf
	v_max_f32_e32 v198, v192, v197
	v_sub_f32_e32 v199, v192, v198
	v_sub_f32_e32 v200, v197, v198
	v_exp_f32_e32 v199, v199
	v_exp_f32_e32 v200, v200
	v_mov_b32_e32 v192, v198
	v_fma_f32 v193, v193, v199, v200
	v_mul_f32_e32 v168, v168, v199
	v_mul_f32_e32 v169, v169, v199
	v_mul_f32_e32 v170, v170, v199
	v_mul_f32_e32 v171, v171, v199
	v_mul_f32_e32 v172, v172, v199
	v_mul_f32_e32 v173, v173, v199
	v_mul_f32_e32 v174, v174, v199
	v_mul_f32_e32 v175, v175, v199
	v_fmac_f32_e32 v168, v200, v136
	v_fmac_f32_e32 v169, v200, v137
	v_fmac_f32_e32 v170, v200, v138
	v_fmac_f32_e32 v171, v200, v139
	v_fmac_f32_e32 v172, v200, v140
	v_fmac_f32_e32 v173, v200, v141
	v_fmac_f32_e32 v174, v200, v142
	v_fmac_f32_e32 v175, v200, v143
	v_mul_f32_e32 v194, 0x43000000, v201
	v_mov_b32_e32 v182, 0xff800000
	v_cndmask_b32_e32 v194, v182, v194, vcc
	s_cmp_eq_u32 s43, 2
	s_cbranch_scc0 .Las_p1b
	v_mov_b32_e32 v194, v182
.Las_p1b:
	v_fma_f32 v197, v160, v144, v194
	v_fmac_f32_e32 v197, v161, v145
	v_fmac_f32_e32 v197, v162, v146
	v_fmac_f32_e32 v197, v163, v147
	v_fmac_f32_e32 v197, v164, v148
	v_fmac_f32_e32 v197, v165, v149
	v_fmac_f32_e32 v197, v166, v150
	v_fmac_f32_e32 v197, v167, v151
	s_nop 1
	v_add_f32_dpp v197, v197, v197 row_ror:8 row_mask:0xf bank_mask:0xf
	s_nop 1
	v_add_f32_dpp v197, v197, v197 row_ror:4 row_mask:0xf bank_mask:0xf
	s_nop 1
	v_add_f32_dpp v197, v197, v197 row_ror:2 row_mask:0xf bank_mask:0xf
	s_nop 1
	v_add_f32_dpp v197, v197, v197 row_ror:1 row_mask:0xf bank_mask:0xf
	v_max_f32_e32 v198, v192, v197
	v_sub_f32_e32 v199, v192, v198
	v_sub_f32_e32 v200, v197, v198
	v_exp_f32_e32 v199, v199
	v_exp_f32_e32 v200, v200
	v_mov_b32_e32 v192, v198
	v_fma_f32 v193, v193, v199, v200
	v_mul_f32_e32 v168, v168, v199
	v_mul_f32_e32 v169, v169, v199
	v_mul_f32_e32 v170, v170, v199
	v_mul_f32_e32 v171, v171, v199
	v_mul_f32_e32 v172, v172, v199
	v_mul_f32_e32 v173, v173, v199
	v_mul_f32_e32 v174, v174, v199
	v_mul_f32_e32 v175, v175, v199
	v_fmac_f32_e32 v168, v200, v152
	v_fmac_f32_e32 v169, v200, v153
	v_fmac_f32_e32 v170, v200, v154
	v_fmac_f32_e32 v171, v200, v155
	v_fmac_f32_e32 v172, v200, v156
	v_fmac_f32_e32 v173, v200, v157
	v_fmac_f32_e32 v174, v200, v158
	v_fmac_f32_e32 v175, v200, v159
	v_add_f32_e32 v194, 4.0, v202
	v_mul_f32_e32 v194, v194, v201
	s_mov_b32 s33, 0
	s_cmp_eq_u32 s43, 2
	s_cbranch_scc0 .Las_slot1
	v_mov_b32_e32 v128, v194
	v_mov_b32_e32 v129, v196
	v_lshlrev_b32_e32 v130, 12, v183
	v_sub_u32_e32 v130, v203, v130
	v_mov_b32_e32 v194, v179
	v_mov_b32_e32 v196, v181
	v_mov_b32_e32 v177, v130
	v_mov_b32_e32 v179, v128
	v_mov_b32_e32 v181, v129
	s_branch .Las_tripR

; __device__ __forceinline__ void attn_sample_item(const P& p, int wi, int lane) {
;     ...
;     for (int g = 0; g < 3; ++g) {
;         const int d = 1 << (2 * g);
; #pragma unroll 3
;         for (int jj = 0; jj < 33; ++jj) {
;             const int j = 4 * jj + kg; const bool valid = j <= 128; const int jc = valid ? j : 128;
;             const int idx = 2048 + i - d * jc;
;             f32x4 k0, k1, v0, v1;
;             if (idx < 2048) { const size_t off = (((size_t)bs * 2048 + idx) * 8 + h) * 128 + 8 * li;
;                 k0 = __builtin_nontemporal_load((const f32x4*)(p.cache_k + off)); k1 = __builtin_nontemporal_load((const f32x4*)(p.cache_k + off + 4)); v0 = __builtin_nontemporal_load((const f32x4*)(p.cache_v + off)); v1 = __builtin_nontemporal_load((const f32x4*)(p.cache_v + off + 4)); }
;             else { const int nr = bs * 4 + (idx - 2048); const float rsn = rstd1[TP + nr]; const int c0 = 4096 + h * 128 + 8 * li;
;                 k0 = acc1_4(ACC1, nr, c0) * rsn; k1 = acc1_4(ACC1, nr, c0 + 4) * rsn; v0 = acc1_4(ACC1, nr, c0 + 1024) * rsn; v1 = acc1_4(ACC1, nr, c0 + 1028) * rsn; }
.Las_sw1R:
	s_cmp_eq_u32 s33, 7
	s_cbranch_scc0 .Las_sw2R
	v_mov_b32_e32 v195, v177
	s_mov_b32 s42, 0xffffc000

; __device__ __forceinline__ float fexp2(float x) { return __builtin_amdgcn_exp2f(x); }
; __device__ __forceinline__ void attn_sample_item(const P& p, int wi, int lane) {
;     ...
;         for (int jj = 0; jj < 33; ++jj) {
;             const int j = 4 * jj + kg; const bool valid = j <= 128; const int jc = valid ? j : 128;
;             const int idx = 2048 + i - d * jc;
;             f32x4 k0, k1, v0, v1;
;             if (idx < 2048) { const size_t off = (((size_t)bs * 2048 + idx) * 8 + h) * 128 + 8 * li;
;                 k0 = __builtin_nontemporal_load((const f32x4*)(p.cache_k + off)); k1 = __builtin_nontemporal_load((const f32x4*)(p.cache_k + off + 4)); v0 = __builtin_nontemporal_load((const f32x4*)(p.cache_v + off)); v1 = __builtin_nontemporal_load((const f32x4*)(p.cache_v + off + 4)); }
;             else { const int nr = bs * 4 + (idx - 2048); const float rsn = rstd1[TP + nr]; const int c0 = 4096 + h * 128 + 8 * li;
;                 k0 = acc1_4(ACC1, nr, c0) * rsn; k1 = acc1_4(ACC1, nr, c0 + 4) * rsn; v0 = acc1_4(ACC1, nr, c0 + 1024) * rsn; v1 = acc1_4(ACC1, nr, c0 + 1028) * rsn; }
;             float dot = (q[0] * k0[0] + q[1] * k0[1]) + (q[2] * k0[2] + q[3] * k0[3]) + (q[4] * k1[0] + q[5] * k1[1]) + (q[6] * k1[2] + q[7] * k1[3]);
;             dot += __shfl_xor(dot, 1); dot += __shfl_xor(dot, 2); dot += __shfl_xor(dot, 4); dot += __shfl_xor(dot, 8);
;             const float s = valid ? dot - sl * (float)(d * j) : -INFINITY;
;             const float mn = fmaxf(m, s), sc = fexp2(m - mn), pe = fexp2(s - mn);
;             l = l * sc + pe;
;             acc[0] = acc[0] * sc + pe * v0[0]; acc[1] = acc[1] * sc + pe * v0[1]; acc[2] = acc[2] * sc + pe * v0[2]; acc[3] = acc[3] * sc + pe * v0[3];
;             acc[4] = acc[4] * sc + pe * v1[0]; acc[5] = acc[5] * sc + pe * v1[1]; acc[6] = acc[6] * sc + pe * v1[2]; acc[7] = acc[7] * sc + pe * v1[3];
;             m = mn;
;         }
.Las_sw4R:
	s_waitcnt vmcnt(28)
	v_fma_f32 v197, v160, v0, v194
	v_fmac_f32_e32 v197, v161, v1
	v_fmac_f32_e32 v197, v162, v2
	v_fmac_f32_e32 v197, v163, v3
	v_fmac_f32_e32 v197, v164, v4
	v_fmac_f32_e32 v197, v165, v5
	v_fmac_f32_e32 v197, v166, v6
	v_fmac_f32_e32 v197, v167, v7
	s_nop 1
	v_add_f32_dpp v197, v197, v197 row_ror:8 row_mask:0xf bank_mask:0xf
	s_nop 1
	v_add_f32_dpp v197, v197, v197 row_ror:4 row_mask:0xf bank_mask:0xf
	s_nop 1
	v_add_f32_dpp v197, v197, v197 row_ror:2 row_mask:0xf bank_mask:0xf
	s_nop 1
	v_add_f32_dpp v197, v197, v197 row_ror:1 row_mask:0xf bank_mask:0xf
	v_max_f32_e32 v198, v192, v197
	v_sub_f32_e32 v199, v192, v198
	v_sub_f32_e32 v200, v197, v198
	v_exp_f32_e32 v199, v199
	v_exp_f32_e32 v200, v200
	v_mov_b32_e32 v192, v198
	v_fma_f32 v193, v193, v199, v200
	v_mul_f32_e32 v168, v168, v199
	v_mul_f32_e32 v169, v169, v199
	v_mul_f32_e32 v170, v170, v199
	v_mul_f32_e32 v171, v171, v199
	v_mul_f32_e32 v172, v172, v199
	v_mul_f32_e32 v173, v173, v199
	v_mul_f32_e32 v174, v174, v199
	v_mul_f32_e32 v175, v175, v199
	v_fmac_f32_e32 v168, v200, v8
	v_fmac_f32_e32 v169, v200, v9
	v_fmac_f32_e32 v170, v200, v10
	v_fmac_f32_e32 v171, v200, v11
	v_fmac_f32_e32 v172, v200, v12
	v_fmac_f32_e32 v173, v200, v13
	v_fmac_f32_e32 v174, v200, v14
	v_fmac_f32_e32 v175, v200, v15
	v_add_f32_e32 v194, v194, v196
	v_add_u32_e32 v195, s42, v195
	global_load_dwordx4 v[0:3], v195, s[20:21] nt
	global_load_dwordx4 v[4:7], v195, s[20:21] offset:256 nt
	global_load_dwordx4 v[8:11], v195, s[24:25] nt
	global_load_dwordx4 v[12:15], v195, s[24:25] offset:256 nt
	s_waitcnt vmcnt(28)
	v_fma_f32 v197, v160, v16, v194
	v_fmac_f32_e32 v197, v161, v17
	v_fmac_f32_e32 v197, v162, v18
	v_fmac_f32_e32 v197, v163, v19
	v_fmac_f32_e32 v197, v164, v20
	v_fmac_f32_e32 v197, v165, v21
	v_fmac_f32_e32 v197, v166, v22
	v_fmac_f32_e32 v197, v167, v23
	s_nop 1
	v_add_f32_dpp v197, v197, v197 row_ror:8 row_mask:0xf bank_mask:0xf
	s_nop 1
	v_add_f32_dpp v197, v197, v197 row_ror:4 row_mask:0xf bank_mask:0xf
	s_nop 1
	v_add_f32_dpp v197, v197, v197 row_ror:2 row_mask:0xf bank_mask:0xf
	s_nop 1
	v_add_f32_dpp v197, v197, v197 row_ror:1 row_mask:0xf bank_mask:0xf
	v_max_f32_e32 v198, v192, v197
	v_sub_f32_e32 v199, v192, v198
	v_sub_f32_e32 v200, v197, v198
	v_exp_f32_e32 v199, v199
	v_exp_f32_e32 v200, v200
	v_mov_b32_e32 v192, v198
	v_fma_f32 v193, v193, v199, v200
	v_mul_f32_e32 v168, v168, v199
	v_mul_f32_e32 v169, v169, v199
	v_mul_f32_e32 v170, v170, v199
	v_mul_f32_e32 v171, v171, v199
	v_mul_f32_e32 v172, v172, v199
	v_mul_f32_e32 v173, v173, v199
	v_mul_f32_e32 v174, v174, v199
	v_mul_f32_e32 v175, v175, v199
	v_fmac_f32_e32 v168, v200, v24
	v_fmac_f32_e32 v169, v200, v25
	v_fmac_f32_e32 v170, v200, v26
	v_fmac_f32_e32 v171, v200, v27
	v_fmac_f32_e32 v172, v200, v28
	v_fmac_f32_e32 v173, v200, v29
	v_fmac_f32_e32 v174, v200, v30
	v_fmac_f32_e32 v175, v200, v31
	v_add_f32_e32 v194, v194, v196
	v_add_u32_e32 v195, s42, v195
	global_load_dwordx4 v[16:19], v195, s[20:21] nt
	global_load_dwordx4 v[20:23], v195, s[20:21] offset:256 nt
	global_load_dwordx4 v[24:27], v195, s[24:25] nt
	global_load_dwordx4 v[28:31], v195, s[24:25] offset:256 nt
	s_waitcnt vmcnt(28)
	v_fma_f32 v197, v160, v32, v194
	v_fmac_f32_e32 v197, v161, v33
	v_fmac_f32_e32 v197, v162, v34
	v_fmac_f32_e32 v197, v163, v35
	v_fmac_f32_e32 v197, v164, v36
	v_fmac_f32_e32 v197, v165, v37
	v_fmac_f32_e32 v197, v166, v38
	v_fmac_f32_e32 v197, v167, v39
	s_nop 1
	v_add_f32_dpp v197, v197, v197 row_ror:8 row_mask:0xf bank_mask:0xf
	s_nop 1
	v_add_f32_dpp v197, v197, v197 row_ror:4 row_mask:0xf bank_mask:0xf
	s_nop 1
	v_add_f32_dpp v197, v197, v197 row_ror:2 row_mask:0xf bank_mask:0xf
	s_nop 1
	v_add_f32_dpp v197, v197, v197 row_ror:1 row_mask:0xf bank_mask:0xf
	v_max_f32_e32 v198, v192, v197
	v_sub_f32_e32 v199, v192, v198
	v_sub_f32_e32 v200, v197, v198
	v_exp_f32_e32 v199, v199
	v_exp_f32_e32 v200, v200
	v_mov_b32_e32 v192, v198
	v_fma_f32 v193, v193, v199, v200
	v_mul_f32_e32 v168, v168, v199
	v_mul_f32_e32 v169, v169, v199
	v_mul_f32_e32 v170, v170, v199
	v_mul_f32_e32 v171, v171, v199
	v_mul_f32_e32 v172, v172, v199
	v_mul_f32_e32 v173, v173, v199
	v_mul_f32_e32 v174, v174, v199
	v_mul_f32_e32 v175, v175, v199
	v_fmac_f32_e32 v168, v200, v40
	v_fmac_f32_e32 v169, v200, v41
	v_fmac_f32_e32 v170, v200, v42
	v_fmac_f32_e32 v171, v200, v43
	v_fmac_f32_e32 v172, v200, v44
	v_fmac_f32_e32 v173, v200, v45
	v_fmac_f32_e32 v174, v200, v46
	v_fmac_f32_e32 v175, v200, v47
	v_add_f32_e32 v194, v194, v196
	v_add_u32_e32 v195, s42, v195
	global_load_dwordx4 v[32:35], v195, s[20:21] nt
	global_load_dwordx4 v[36:39], v195, s[20:21] offset:256 nt
	global_load_dwordx4 v[40:43], v195, s[24:25] nt
	global_load_dwordx4 v[44:47], v195, s[24:25] offset:256 nt
	s_waitcnt vmcnt(28)
	v_fma_f32 v197, v160, v48, v194
	v_fmac_f32_e32 v197, v161, v49
	v_fmac_f32_e32 v197, v162, v50
	v_fmac_f32_e32 v197, v163, v51
	v_fmac_f32_e32 v197, v164, v52
	v_fmac_f32_e32 v197, v165, v53
	v_fmac_f32_e32 v197, v166, v54
	v_fmac_f32_e32 v197, v167, v55
	s_nop 1
	v_add_f32_dpp v197, v197, v197 row_ror:8 row_mask:0xf bank_mask:0xf
	s_nop 1
	v_add_f32_dpp v197, v197, v197 row_ror:4 row_mask:0xf bank_mask:0xf
	s_nop 1
	v_add_f32_dpp v197, v197, v197 row_ror:2 row_mask:0xf bank_mask:0xf
	s_nop 1
	v_add_f32_dpp v197, v197, v197 row_ror:1 row_mask:0xf bank_mask:0xf
	v_max_f32_e32 v198, v192, v197
	v_sub_f32_e32 v199, v192, v198
	v_sub_f32_e32 v200, v197, v198
	v_exp_f32_e32 v199, v199
	v_exp_f32_e32 v200, v200
	v_mov_b32_e32 v192, v198
	v_fma_f32 v193, v193, v199, v200
	v_mul_f32_e32 v168, v168, v199
	v_mul_f32_e32 v169, v169, v199
	v_mul_f32_e32 v170, v170, v199
	v_mul_f32_e32 v171, v171, v199
	v_mul_f32_e32 v172, v172, v199
	v_mul_f32_e32 v173, v173, v199
	v_mul_f32_e32 v174, v174, v199
	v_mul_f32_e32 v175, v175, v199
	v_fmac_f32_e32 v168, v200, v56
	v_fmac_f32_e32 v169, v200, v57
	v_fmac_f32_e32 v170, v200, v58
	v_fmac_f32_e32 v171, v200, v59
	v_fmac_f32_e32 v172, v200, v60
	v_fmac_f32_e32 v173, v200, v61
	v_fmac_f32_e32 v174, v200, v62
	v_fmac_f32_e32 v175, v200, v63
	v_add_f32_e32 v194, v194, v196
	v_add_u32_e32 v195, s42, v195
	global_load_dwordx4 v[48:51], v195, s[20:21] nt
	global_load_dwordx4 v[52:55], v195, s[20:21] offset:256 nt
	global_load_dwordx4 v[56:59], v195, s[24:25] nt
	global_load_dwordx4 v[60:63], v195, s[24:25] offset:256 nt
	s_waitcnt vmcnt(28)
; __device__ __forceinline__ float fexp2(float x) { return __builtin_amdgcn_exp2f(x); }
; __device__ __forceinline__ void attn_sample_item(const P& p, int wi, int lane) {
;     ...
;         for (int jj = 0; jj < 33; ++jj) {
;             const int j = 4 * jj + kg; const bool valid = j <= 128; const int jc = valid ? j : 128;
;             const int idx = 2048 + i - d * jc;
;             f32x4 k0, k1, v0, v1;
;             if (idx < 2048) { const size_t off = (((size_t)bs * 2048 + idx) * 8 + h) * 128 + 8 * li;
;                 k0 = __builtin_nontemporal_load((const f32x4*)(p.cache_k + off)); k1 = __builtin_nontemporal_load((const f32x4*)(p.cache_k + off + 4)); v0 = __builtin_nontemporal_load((const f32x4*)(p.cache_v + off)); v1 = __builtin_nontemporal_load((const f32x4*)(p.cache_v + off + 4)); }
;             else { const int nr = bs * 4 + (idx - 2048); const float rsn = rstd1[TP + nr]; const int c0 = 4096 + h * 128 + 8 * li;
;                 k0 = acc1_4(ACC1, nr, c0) * rsn; k1 = acc1_4(ACC1, nr, c0 + 4) * rsn; v0 = acc1_4(ACC1, nr, c0 + 1024) * rsn; v1 = acc1_4(ACC1, nr, c0 + 1028) * rsn; }
;             float dot = (q[0] * k0[0] + q[1] * k0[1]) + (q[2] * k0[2] + q[3] * k0[3]) + (q[4] * k1[0] + q[5] * k1[1]) + (q[6] * k1[2] + q[7] * k1[3]);
;             dot += __shfl_xor(dot, 1); dot += __shfl_xor(dot, 2); dot += __shfl_xor(dot, 4); dot += __shfl_xor(dot, 8);
;             const float s = valid ? dot - sl * (float)(d * j) : -INFINITY;
;             const float mn = fmaxf(m, s), sc = fexp2(m - mn), pe = fexp2(s - mn);
;             l = l * sc + pe;
;             acc[0] = acc[0] * sc + pe * v0[0]; acc[1] = acc[1] * sc + pe * v0[1]; acc[2] = acc[2] * sc + pe * v0[2]; acc[3] = acc[3] * sc + pe * v0[3];
;             acc[4] = acc[4] * sc + pe * v1[0]; acc[5] = acc[5] * sc + pe * v1[1]; acc[6] = acc[6] * sc + pe * v1[2]; acc[7] = acc[7] * sc + pe * v1[3];
;             m = mn;
;         }
	v_fma_f32 v197, v160, v64, v194
	v_fmac_f32_e32 v197, v161, v65
	v_fmac_f32_e32 v197, v162, v66
	v_fmac_f32_e32 v197, v163, v67
	v_fmac_f32_e32 v197, v164, v68
	v_fmac_f32_e32 v197, v165, v69
	v_fmac_f32_e32 v197, v166, v70
	v_fmac_f32_e32 v197, v167, v71
	s_nop 1
	v_add_f32_dpp v197, v197, v197 row_ror:8 row_mask:0xf bank_mask:0xf
	s_nop 1
	v_add_f32_dpp v197, v197, v197 row_ror:4 row_mask:0xf bank_mask:0xf
	s_nop 1
	v_add_f32_dpp v197, v197, v197 row_ror:2 row_mask:0xf bank_mask:0xf
	s_nop 1
	v_add_f32_dpp v197, v197, v197 row_ror:1 row_mask:0xf bank_mask:0xf
	v_max_f32_e32 v198, v192, v197
	v_sub_f32_e32 v199, v192, v198
	v_sub_f32_e32 v200, v197, v198
	v_exp_f32_e32 v199, v199
	v_exp_f32_e32 v200, v200
	v_mov_b32_e32 v192, v198
	v_fma_f32 v193, v193, v199, v200
	v_mul_f32_e32 v168, v168, v199
	v_mul_f32_e32 v169, v169, v199
	v_mul_f32_e32 v170, v170, v199
	v_mul_f32_e32 v171, v171, v199
	v_mul_f32_e32 v172, v172, v199
	v_mul_f32_e32 v173, v173, v199
	v_mul_f32_e32 v174, v174, v199
	v_mul_f32_e32 v175, v175, v199
	v_fmac_f32_e32 v168, v200, v72
	v_fmac_f32_e32 v169, v200, v73
	v_fmac_f32_e32 v170, v200, v74
	v_fmac_f32_e32 v171, v200, v75
	v_fmac_f32_e32 v172, v200, v76
	v_fmac_f32_e32 v173, v200, v77
	v_fmac_f32_e32 v174, v200, v78
	v_fmac_f32_e32 v175, v200, v79
	v_add_f32_e32 v194, v194, v196
	v_add_u32_e32 v195, s42, v195
	global_load_dwordx4 v[64:67], v195, s[20:21] nt
	global_load_dwordx4 v[68:71], v195, s[20:21] offset:256 nt
	global_load_dwordx4 v[72:75], v195, s[24:25] nt
	global_load_dwordx4 v[76:79], v195, s[24:25] offset:256 nt
	s_waitcnt vmcnt(28)
	v_fma_f32 v197, v160, v80, v194
	v_fmac_f32_e32 v197, v161, v81
	v_fmac_f32_e32 v197, v162, v82
	v_fmac_f32_e32 v197, v163, v83
	v_fmac_f32_e32 v197, v164, v84
	v_fmac_f32_e32 v197, v165, v85
	v_fmac_f32_e32 v197, v166, v86
	v_fmac_f32_e32 v197, v167, v87
	s_nop 1
	v_add_f32_dpp v197, v197, v197 row_ror:8 row_mask:0xf bank_mask:0xf
	s_nop 1
	v_add_f32_dpp v197, v197, v197 row_ror:4 row_mask:0xf bank_mask:0xf
	s_nop 1
	v_add_f32_dpp v197, v197, v197 row_ror:2 row_mask:0xf bank_mask:0xf
	s_nop 1
	v_add_f32_dpp v197, v197, v197 row_ror:1 row_mask:0xf bank_mask:0xf
	v_max_f32_e32 v198, v192, v197
	v_sub_f32_e32 v199, v192, v198
	v_sub_f32_e32 v200, v197, v198
	v_exp_f32_e32 v199, v199
	v_exp_f32_e32 v200, v200
	v_mov_b32_e32 v192, v198
	v_fma_f32 v193, v193, v199, v200
	v_mul_f32_e32 v168, v168, v199
	v_mul_f32_e32 v169, v169, v199
	v_mul_f32_e32 v170, v170, v199
	v_mul_f32_e32 v171, v171, v199
	v_mul_f32_e32 v172, v172, v199
	v_mul_f32_e32 v173, v173, v199
	v_mul_f32_e32 v174, v174, v199
	v_mul_f32_e32 v175, v175, v199
	v_fmac_f32_e32 v168, v200, v88
	v_fmac_f32_e32 v169, v200, v89
	v_fmac_f32_e32 v170, v200, v90
	v_fmac_f32_e32 v171, v200, v91
	v_fmac_f32_e32 v172, v200, v92
	v_fmac_f32_e32 v173, v200, v93
	v_fmac_f32_e32 v174, v200, v94
	v_fmac_f32_e32 v175, v200, v95
	v_add_f32_e32 v194, v194, v196
	v_add_u32_e32 v195, s42, v195
	global_load_dwordx4 v[80:83], v195, s[20:21] nt
	global_load_dwordx4 v[84:87], v195, s[20:21] offset:256 nt
	global_load_dwordx4 v[88:91], v195, s[24:25] nt
	global_load_dwordx4 v[92:95], v195, s[24:25] offset:256 nt
	s_waitcnt vmcnt(28)
	v_fma_f32 v197, v160, v96, v194
	v_fmac_f32_e32 v197, v161, v97
	v_fmac_f32_e32 v197, v162, v98
	v_fmac_f32_e32 v197, v163, v99
	v_fmac_f32_e32 v197, v164, v100
	v_fmac_f32_e32 v197, v165, v101
	v_fmac_f32_e32 v197, v166, v102
	v_fmac_f32_e32 v197, v167, v103
	s_nop 1
	v_add_f32_dpp v197, v197, v197 row_ror:8 row_mask:0xf bank_mask:0xf
	s_nop 1
	v_add_f32_dpp v197, v197, v197 row_ror:4 row_mask:0xf bank_mask:0xf
	s_nop 1
	v_add_f32_dpp v197, v197, v197 row_ror:2 row_mask:0xf bank_mask:0xf
	s_nop 1
	v_add_f32_dpp v197, v197, v197 row_ror:1 row_mask:0xf bank_mask:0xf
	v_max_f32_e32 v198, v192, v197
	v_sub_f32_e32 v199, v192, v198
	v_sub_f32_e32 v200, v197, v198
	v_exp_f32_e32 v199, v199
	v_exp_f32_e32 v200, v200
	v_mov_b32_e32 v192, v198
	v_fma_f32 v193, v193, v199, v200
	v_mul_f32_e32 v168, v168, v199
	v_mul_f32_e32 v169, v169, v199
	v_mul_f32_e32 v170, v170, v199
	v_mul_f32_e32 v171, v171, v199
	v_mul_f32_e32 v172, v172, v199
	v_mul_f32_e32 v173, v173, v199
	v_mul_f32_e32 v174, v174, v199
	v_mul_f32_e32 v175, v175, v199
	v_fmac_f32_e32 v168, v200, v104
	v_fmac_f32_e32 v169, v200, v105
	v_fmac_f32_e32 v170, v200, v106
	v_fmac_f32_e32 v171, v200, v107
	v_fmac_f32_e32 v172, v200, v108
	v_fmac_f32_e32 v173, v200, v109
	v_fmac_f32_e32 v174, v200, v110
	v_fmac_f32_e32 v175, v200, v111
	v_add_f32_e32 v194, v194, v196
	v_add_u32_e32 v195, s42, v195
	global_load_dwordx4 v[96:99], v195, s[20:21] nt
	global_load_dwordx4 v[100:103], v195, s[20:21] offset:256 nt
	global_load_dwordx4 v[104:107], v195, s[24:25] nt
	global_load_dwordx4 v[108:111], v195, s[24:25] offset:256 nt
	s_waitcnt vmcnt(28)
	v_fma_f32 v197, v160, v112, v194
	v_fmac_f32_e32 v197, v161, v113
	v_fmac_f32_e32 v197, v162, v114
	v_fmac_f32_e32 v197, v163, v115
	v_fmac_f32_e32 v197, v164, v116
	v_fmac_f32_e32 v197, v165, v117
	v_fmac_f32_e32 v197, v166, v118
	v_fmac_f32_e32 v197, v167, v119
	s_nop 1
	v_add_f32_dpp v197, v197, v197 row_ror:8 row_mask:0xf bank_mask:0xf
	s_nop 1
	v_add_f32_dpp v197, v197, v197 row_ror:4 row_mask:0xf bank_mask:0xf
	s_nop 1
	v_add_f32_dpp v197, v197, v197 row_ror:2 row_mask:0xf bank_mask:0xf
	s_nop 1
	v_add_f32_dpp v197, v197, v197 row_ror:1 row_mask:0xf bank_mask:0xf
	v_max_f32_e32 v198, v192, v197
	v_sub_f32_e32 v199, v192, v198
	v_sub_f32_e32 v200, v197, v198
	v_exp_f32_e32 v199, v199
	v_exp_f32_e32 v200, v200
	v_mov_b32_e32 v192, v198
	v_fma_f32 v193, v193, v199, v200
	v_mul_f32_e32 v168, v168, v199
	v_mul_f32_e32 v169, v169, v199
	v_mul_f32_e32 v170, v170, v199
	v_mul_f32_e32 v171, v171, v199
	v_mul_f32_e32 v172, v172, v199
	v_mul_f32_e32 v173, v173, v199
	v_mul_f32_e32 v174, v174, v199
	v_mul_f32_e32 v175, v175, v199
	v_fmac_f32_e32 v168, v200, v120
	v_fmac_f32_e32 v169, v200, v121
	v_fmac_f32_e32 v170, v200, v122
	v_fmac_f32_e32 v171, v200, v123
	v_fmac_f32_e32 v172, v200, v124
	v_fmac_f32_e32 v173, v200, v125
	v_fmac_f32_e32 v174, v200, v126
	v_fmac_f32_e32 v175, v200, v127
	v_add_f32_e32 v194, v194, v196
	v_add_u32_e32 v195, s42, v195
	global_load_dwordx4 v[112:115], v195, s[20:21] nt
	global_load_dwordx4 v[116:119], v195, s[20:21] offset:256 nt
	global_load_dwordx4 v[120:123], v195, s[24:25] nt
	global_load_dwordx4 v[124:127], v195, s[24:25] offset:256 nt
	s_add_u32 s33, s33, 1
	s_cmp_lt_u32 s33, 7
	s_cbranch_scc1 .Las_tripR

; __device__ __forceinline__ float fexp2(float x) { return __builtin_amdgcn_exp2f(x); }
; __device__ __forceinline__ void attn_sample_item(const P& p, int wi, int lane) {
;     ...
;         for (int jj = 0; jj < 33; ++jj) {
;             const int j = 4 * jj + kg; const bool valid = j <= 128; const int jc = valid ? j : 128;
;             const int idx = 2048 + i - d * jc;
;             f32x4 k0, k1, v0, v1;
;             if (idx < 2048) { const size_t off = (((size_t)bs * 2048 + idx) * 8 + h) * 128 + 8 * li;
;                 k0 = __builtin_nontemporal_load((const f32x4*)(p.cache_k + off)); k1 = __builtin_nontemporal_load((const f32x4*)(p.cache_k + off + 4)); v0 = __builtin_nontemporal_load((const f32x4*)(p.cache_v + off)); v1 = __builtin_nontemporal_load((const f32x4*)(p.cache_v + off + 4)); }
;             else { const int nr = bs * 4 + (idx - 2048); const float rsn = rstd1[TP + nr]; const int c0 = 4096 + h * 128 + 8 * li;
;                 k0 = acc1_4(ACC1, nr, c0) * rsn; k1 = acc1_4(ACC1, nr, c0 + 4) * rsn; v0 = acc1_4(ACC1, nr, c0 + 1024) * rsn; v1 = acc1_4(ACC1, nr, c0 + 1028) * rsn; }
;             float dot = (q[0] * k0[0] + q[1] * k0[1]) + (q[2] * k0[2] + q[3] * k0[3]) + (q[4] * k1[0] + q[5] * k1[1]) + (q[6] * k1[2] + q[7] * k1[3]);
;             dot += __shfl_xor(dot, 1); dot += __shfl_xor(dot, 2); dot += __shfl_xor(dot, 4); dot += __shfl_xor(dot, 8);
;             const float s = valid ? dot - sl * (float)(d * j) : -INFINITY;
;             const float mn = fmaxf(m, s), sc = fexp2(m - mn), pe = fexp2(s - mn);
;             l = l * sc + pe;
;             acc[0] = acc[0] * sc + pe * v0[0]; acc[1] = acc[1] * sc + pe * v0[1]; acc[2] = acc[2] * sc + pe * v0[2]; acc[3] = acc[3] * sc + pe * v0[3];
;             acc[4] = acc[4] * sc + pe * v1[0]; acc[5] = acc[5] * sc + pe * v1[1]; acc[6] = acc[6] * sc + pe * v1[2]; acc[7] = acc[7] * sc + pe * v1[3];
;             m = mn;
;         }
.Las_sw4R2:
	s_waitcnt vmcnt(28)
	v_fma_f32 v197, v160, v0, v194
	v_fmac_f32_e32 v197, v161, v1
	v_fmac_f32_e32 v197, v162, v2
	v_fmac_f32_e32 v197, v163, v3
	v_fmac_f32_e32 v197, v164, v4
	v_fmac_f32_e32 v197, v165, v5
	v_fmac_f32_e32 v197, v166, v6
	v_fmac_f32_e32 v197, v167, v7
	s_nop 1
	v_add_f32_dpp v197, v197, v197 row_ror:8 row_mask:0xf bank_mask:0xf
	s_nop 1
	v_add_f32_dpp v197, v197, v197 row_ror:4 row_mask:0xf bank_mask:0xf
	s_nop 1
	v_add_f32_dpp v197, v197, v197 row_ror:2 row_mask:0xf bank_mask:0xf
	s_nop 1
	v_add_f32_dpp v197, v197, v197 row_ror:1 row_mask:0xf bank_mask:0xf
	v_max_f32_e32 v198, v192, v197
	v_sub_f32_e32 v199, v192, v198
	v_sub_f32_e32 v200, v197, v198
	v_exp_f32_e32 v199, v199
	v_exp_f32_e32 v200, v200
	v_mov_b32_e32 v192, v198
	v_fma_f32 v193, v193, v199, v200
	v_mul_f32_e32 v168, v168, v199
	v_mul_f32_e32 v169, v169, v199
	v_mul_f32_e32 v170, v170, v199
	v_mul_f32_e32 v171, v171, v199
	v_mul_f32_e32 v172, v172, v199
	v_mul_f32_e32 v173, v173, v199
	v_mul_f32_e32 v174, v174, v199
	v_mul_f32_e32 v175, v175, v199
	v_fmac_f32_e32 v168, v200, v8
	v_fmac_f32_e32 v169, v200, v9
	v_fmac_f32_e32 v170, v200, v10
	v_fmac_f32_e32 v171, v200, v11
	v_fmac_f32_e32 v172, v200, v12
	v_fmac_f32_e32 v173, v200, v13
	v_fmac_f32_e32 v174, v200, v14
	v_fmac_f32_e32 v175, v200, v15
	v_add_f32_e32 v194, v194, v196
	v_add_u32_e32 v195, s42, v195
	global_load_dwordx4 v[0:3], v195, s[20:21]
	global_load_dwordx4 v[4:7], v195, s[20:21] offset:256
	global_load_dwordx4 v[8:11], v195, s[24:25]
	global_load_dwordx4 v[12:15], v195, s[24:25] offset:256
	s_waitcnt vmcnt(28)
	v_fma_f32 v197, v160, v16, v194
	v_fmac_f32_e32 v197, v161, v17
	v_fmac_f32_e32 v197, v162, v18
	v_fmac_f32_e32 v197, v163, v19
	v_fmac_f32_e32 v197, v164, v20
	v_fmac_f32_e32 v197, v165, v21
	v_fmac_f32_e32 v197, v166, v22
	v_fmac_f32_e32 v197, v167, v23
	s_nop 1
	v_add_f32_dpp v197, v197, v197 row_ror:8 row_mask:0xf bank_mask:0xf
	s_nop 1
	v_add_f32_dpp v197, v197, v197 row_ror:4 row_mask:0xf bank_mask:0xf
	s_nop 1
	v_add_f32_dpp v197, v197, v197 row_ror:2 row_mask:0xf bank_mask:0xf
	s_nop 1
	v_add_f32_dpp v197, v197, v197 row_ror:1 row_mask:0xf bank_mask:0xf
	v_max_f32_e32 v198, v192, v197
	v_sub_f32_e32 v199, v192, v198
	v_sub_f32_e32 v200, v197, v198
	v_exp_f32_e32 v199, v199
	v_exp_f32_e32 v200, v200
	v_mov_b32_e32 v192, v198
	v_fma_f32 v193, v193, v199, v200
	v_mul_f32_e32 v168, v168, v199
	v_mul_f32_e32 v169, v169, v199
	v_mul_f32_e32 v170, v170, v199
	v_mul_f32_e32 v171, v171, v199
	v_mul_f32_e32 v172, v172, v199
	v_mul_f32_e32 v173, v173, v199
	v_mul_f32_e32 v174, v174, v199
	v_mul_f32_e32 v175, v175, v199
	v_fmac_f32_e32 v168, v200, v24
	v_fmac_f32_e32 v169, v200, v25
	v_fmac_f32_e32 v170, v200, v26
	v_fmac_f32_e32 v171, v200, v27
	v_fmac_f32_e32 v172, v200, v28
	v_fmac_f32_e32 v173, v200, v29
	v_fmac_f32_e32 v174, v200, v30
	v_fmac_f32_e32 v175, v200, v31
	v_add_f32_e32 v194, v194, v196
	v_add_u32_e32 v195, s42, v195
	global_load_dwordx4 v[16:19], v195, s[20:21]
	global_load_dwordx4 v[20:23], v195, s[20:21] offset:256
	global_load_dwordx4 v[24:27], v195, s[24:25]
	global_load_dwordx4 v[28:31], v195, s[24:25] offset:256
	s_waitcnt vmcnt(28)
	v_fma_f32 v197, v160, v32, v194
	v_fmac_f32_e32 v197, v161, v33
	v_fmac_f32_e32 v197, v162, v34
	v_fmac_f32_e32 v197, v163, v35
	v_fmac_f32_e32 v197, v164, v36
	v_fmac_f32_e32 v197, v165, v37
	v_fmac_f32_e32 v197, v166, v38
	v_fmac_f32_e32 v197, v167, v39
	s_nop 1
	v_add_f32_dpp v197, v197, v197 row_ror:8 row_mask:0xf bank_mask:0xf
	s_nop 1
	v_add_f32_dpp v197, v197, v197 row_ror:4 row_mask:0xf bank_mask:0xf
	s_nop 1
	v_add_f32_dpp v197, v197, v197 row_ror:2 row_mask:0xf bank_mask:0xf
	s_nop 1
	v_add_f32_dpp v197, v197, v197 row_ror:1 row_mask:0xf bank_mask:0xf
	v_max_f32_e32 v198, v192, v197
	v_sub_f32_e32 v199, v192, v198
	v_sub_f32_e32 v200, v197, v198
	v_exp_f32_e32 v199, v199
	v_exp_f32_e32 v200, v200
	v_mov_b32_e32 v192, v198
	v_fma_f32 v193, v193, v199, v200
	v_mul_f32_e32 v168, v168, v199
	v_mul_f32_e32 v169, v169, v199
	v_mul_f32_e32 v170, v170, v199
	v_mul_f32_e32 v171, v171, v199
	v_mul_f32_e32 v172, v172, v199
	v_mul_f32_e32 v173, v173, v199
	v_mul_f32_e32 v174, v174, v199
	v_mul_f32_e32 v175, v175, v199
	v_fmac_f32_e32 v168, v200, v40
	v_fmac_f32_e32 v169, v200, v41
	v_fmac_f32_e32 v170, v200, v42
	v_fmac_f32_e32 v171, v200, v43
	v_fmac_f32_e32 v172, v200, v44
	v_fmac_f32_e32 v173, v200, v45
	v_fmac_f32_e32 v174, v200, v46
	v_fmac_f32_e32 v175, v200, v47
	v_add_f32_e32 v194, v194, v196
	v_add_u32_e32 v195, s42, v195
	global_load_dwordx4 v[32:35], v195, s[20:21]
	global_load_dwordx4 v[36:39], v195, s[20:21] offset:256
	global_load_dwordx4 v[40:43], v195, s[24:25]
	global_load_dwordx4 v[44:47], v195, s[24:25] offset:256
	s_waitcnt vmcnt(28)
	v_fma_f32 v197, v160, v48, v194
	v_fmac_f32_e32 v197, v161, v49
	v_fmac_f32_e32 v197, v162, v50
	v_fmac_f32_e32 v197, v163, v51
	v_fmac_f32_e32 v197, v164, v52
	v_fmac_f32_e32 v197, v165, v53
	v_fmac_f32_e32 v197, v166, v54
	v_fmac_f32_e32 v197, v167, v55
	s_nop 1
	v_add_f32_dpp v197, v197, v197 row_ror:8 row_mask:0xf bank_mask:0xf
	s_nop 1
	v_add_f32_dpp v197, v197, v197 row_ror:4 row_mask:0xf bank_mask:0xf
	s_nop 1
	v_add_f32_dpp v197, v197, v197 row_ror:2 row_mask:0xf bank_mask:0xf
	s_nop 1
	v_add_f32_dpp v197, v197, v197 row_ror:1 row_mask:0xf bank_mask:0xf
	v_max_f32_e32 v198, v192, v197
	v_sub_f32_e32 v199, v192, v198
	v_sub_f32_e32 v200, v197, v198
	v_exp_f32_e32 v199, v199
	v_exp_f32_e32 v200, v200
	v_mov_b32_e32 v192, v198
	v_fma_f32 v193, v193, v199, v200
	v_mul_f32_e32 v168, v168, v199
	v_mul_f32_e32 v169, v169, v199
	v_mul_f32_e32 v170, v170, v199
	v_mul_f32_e32 v171, v171, v199
	v_mul_f32_e32 v172, v172, v199
	v_mul_f32_e32 v173, v173, v199
	v_mul_f32_e32 v174, v174, v199
	v_mul_f32_e32 v175, v175, v199
	v_fmac_f32_e32 v168, v200, v56
	v_fmac_f32_e32 v169, v200, v57
	v_fmac_f32_e32 v170, v200, v58
	v_fmac_f32_e32 v171, v200, v59
	v_fmac_f32_e32 v172, v200, v60
	v_fmac_f32_e32 v173, v200, v61
	v_fmac_f32_e32 v174, v200, v62
	v_fmac_f32_e32 v175, v200, v63
	v_add_f32_e32 v194, v194, v196
	v_add_u32_e32 v195, s42, v195
	global_load_dwordx4 v[48:51], v195, s[20:21]
	global_load_dwordx4 v[52:55], v195, s[20:21] offset:256
	global_load_dwordx4 v[56:59], v195, s[24:25]
	global_load_dwordx4 v[60:63], v195, s[24:25] offset:256
	s_waitcnt vmcnt(28)
; __device__ __forceinline__ float fexp2(float x) { return __builtin_amdgcn_exp2f(x); }
; __device__ __forceinline__ void attn_sample_item(const P& p, int wi, int lane) {
;     ...
;         for (int jj = 0; jj < 33; ++jj) {
;             const int j = 4 * jj + kg; const bool valid = j <= 128; const int jc = valid ? j : 128;
;             const int idx = 2048 + i - d * jc;
;             f32x4 k0, k1, v0, v1;
;             if (idx < 2048) { const size_t off = (((size_t)bs * 2048 + idx) * 8 + h) * 128 + 8 * li;
;                 k0 = __builtin_nontemporal_load((const f32x4*)(p.cache_k + off)); k1 = __builtin_nontemporal_load((const f32x4*)(p.cache_k + off + 4)); v0 = __builtin_nontemporal_load((const f32x4*)(p.cache_v + off)); v1 = __builtin_nontemporal_load((const f32x4*)(p.cache_v + off + 4)); }
;             else { const int nr = bs * 4 + (idx - 2048); const float rsn = rstd1[TP + nr]; const int c0 = 4096 + h * 128 + 8 * li;
;                 k0 = acc1_4(ACC1, nr, c0) * rsn; k1 = acc1_4(ACC1, nr, c0 + 4) * rsn; v0 = acc1_4(ACC1, nr, c0 + 1024) * rsn; v1 = acc1_4(ACC1, nr, c0 + 1028) * rsn; }
;             float dot = (q[0] * k0[0] + q[1] * k0[1]) + (q[2] * k0[2] + q[3] * k0[3]) + (q[4] * k1[0] + q[5] * k1[1]) + (q[6] * k1[2] + q[7] * k1[3]);
;             dot += __shfl_xor(dot, 1); dot += __shfl_xor(dot, 2); dot += __shfl_xor(dot, 4); dot += __shfl_xor(dot, 8);
;             const float s = valid ? dot - sl * (float)(d * j) : -INFINITY;
;             const float mn = fmaxf(m, s), sc = fexp2(m - mn), pe = fexp2(s - mn);
;             l = l * sc + pe;
;             acc[0] = acc[0] * sc + pe * v0[0]; acc[1] = acc[1] * sc + pe * v0[1]; acc[2] = acc[2] * sc + pe * v0[2]; acc[3] = acc[3] * sc + pe * v0[3];
;             acc[4] = acc[4] * sc + pe * v1[0]; acc[5] = acc[5] * sc + pe * v1[1]; acc[6] = acc[6] * sc + pe * v1[2]; acc[7] = acc[7] * sc + pe * v1[3];
;             m = mn;
;         }
	v_fma_f32 v197, v160, v64, v194
	v_fmac_f32_e32 v197, v161, v65
	v_fmac_f32_e32 v197, v162, v66
	v_fmac_f32_e32 v197, v163, v67
	v_fmac_f32_e32 v197, v164, v68
	v_fmac_f32_e32 v197, v165, v69
	v_fmac_f32_e32 v197, v166, v70
	v_fmac_f32_e32 v197, v167, v71
	s_nop 1
	v_add_f32_dpp v197, v197, v197 row_ror:8 row_mask:0xf bank_mask:0xf
	s_nop 1
	v_add_f32_dpp v197, v197, v197 row_ror:4 row_mask:0xf bank_mask:0xf
	s_nop 1
	v_add_f32_dpp v197, v197, v197 row_ror:2 row_mask:0xf bank_mask:0xf
	s_nop 1
	v_add_f32_dpp v197, v197, v197 row_ror:1 row_mask:0xf bank_mask:0xf
	v_max_f32_e32 v198, v192, v197
	v_sub_f32_e32 v199, v192, v198
	v_sub_f32_e32 v200, v197, v198
	v_exp_f32_e32 v199, v199
	v_exp_f32_e32 v200, v200
	v_mov_b32_e32 v192, v198
	v_fma_f32 v193, v193, v199, v200
	v_mul_f32_e32 v168, v168, v199
	v_mul_f32_e32 v169, v169, v199
	v_mul_f32_e32 v170, v170, v199
	v_mul_f32_e32 v171, v171, v199
	v_mul_f32_e32 v172, v172, v199
	v_mul_f32_e32 v173, v173, v199
	v_mul_f32_e32 v174, v174, v199
	v_mul_f32_e32 v175, v175, v199
	v_fmac_f32_e32 v168, v200, v72
	v_fmac_f32_e32 v169, v200, v73
	v_fmac_f32_e32 v170, v200, v74
	v_fmac_f32_e32 v171, v200, v75
	v_fmac_f32_e32 v172, v200, v76
	v_fmac_f32_e32 v173, v200, v77
	v_fmac_f32_e32 v174, v200, v78
	v_fmac_f32_e32 v175, v200, v79
	v_add_f32_e32 v194, v194, v196
	v_add_u32_e32 v195, s42, v195
	global_load_dwordx4 v[64:67], v195, s[20:21]
	global_load_dwordx4 v[68:71], v195, s[20:21] offset:256
	global_load_dwordx4 v[72:75], v195, s[24:25]
	global_load_dwordx4 v[76:79], v195, s[24:25] offset:256
	s_waitcnt vmcnt(28)
	v_fma_f32 v197, v160, v80, v194
	v_fmac_f32_e32 v197, v161, v81
	v_fmac_f32_e32 v197, v162, v82
	v_fmac_f32_e32 v197, v163, v83
	v_fmac_f32_e32 v197, v164, v84
	v_fmac_f32_e32 v197, v165, v85
	v_fmac_f32_e32 v197, v166, v86
	v_fmac_f32_e32 v197, v167, v87
	s_nop 1
	v_add_f32_dpp v197, v197, v197 row_ror:8 row_mask:0xf bank_mask:0xf
	s_nop 1
	v_add_f32_dpp v197, v197, v197 row_ror:4 row_mask:0xf bank_mask:0xf
	s_nop 1
	v_add_f32_dpp v197, v197, v197 row_ror:2 row_mask:0xf bank_mask:0xf
	s_nop 1
	v_add_f32_dpp v197, v197, v197 row_ror:1 row_mask:0xf bank_mask:0xf
	v_max_f32_e32 v198, v192, v197
	v_sub_f32_e32 v199, v192, v198
	v_sub_f32_e32 v200, v197, v198
	v_exp_f32_e32 v199, v199
	v_exp_f32_e32 v200, v200
	v_mov_b32_e32 v192, v198
	v_fma_f32 v193, v193, v199, v200
	v_mul_f32_e32 v168, v168, v199
	v_mul_f32_e32 v169, v169, v199
	v_mul_f32_e32 v170, v170, v199
	v_mul_f32_e32 v171, v171, v199
	v_mul_f32_e32 v172, v172, v199
	v_mul_f32_e32 v173, v173, v199
	v_mul_f32_e32 v174, v174, v199
	v_mul_f32_e32 v175, v175, v199
	v_fmac_f32_e32 v168, v200, v88
	v_fmac_f32_e32 v169, v200, v89
	v_fmac_f32_e32 v170, v200, v90
	v_fmac_f32_e32 v171, v200, v91
	v_fmac_f32_e32 v172, v200, v92
	v_fmac_f32_e32 v173, v200, v93
	v_fmac_f32_e32 v174, v200, v94
	v_fmac_f32_e32 v175, v200, v95
	v_add_f32_e32 v194, v194, v196
	v_add_u32_e32 v195, s42, v195
	global_load_dwordx4 v[80:83], v195, s[20:21]
	global_load_dwordx4 v[84:87], v195, s[20:21] offset:256
	global_load_dwordx4 v[88:91], v195, s[24:25]
	global_load_dwordx4 v[92:95], v195, s[24:25] offset:256
	s_waitcnt vmcnt(28)
	v_fma_f32 v197, v160, v96, v194
	v_fmac_f32_e32 v197, v161, v97
	v_fmac_f32_e32 v197, v162, v98
	v_fmac_f32_e32 v197, v163, v99
	v_fmac_f32_e32 v197, v164, v100
	v_fmac_f32_e32 v197, v165, v101
	v_fmac_f32_e32 v197, v166, v102
	v_fmac_f32_e32 v197, v167, v103
	s_nop 1
	v_add_f32_dpp v197, v197, v197 row_ror:8 row_mask:0xf bank_mask:0xf
	s_nop 1
	v_add_f32_dpp v197, v197, v197 row_ror:4 row_mask:0xf bank_mask:0xf
	s_nop 1
	v_add_f32_dpp v197, v197, v197 row_ror:2 row_mask:0xf bank_mask:0xf
	s_nop 1
	v_add_f32_dpp v197, v197, v197 row_ror:1 row_mask:0xf bank_mask:0xf
	v_max_f32_e32 v198, v192, v197
	v_sub_f32_e32 v199, v192, v198
	v_sub_f32_e32 v200, v197, v198
	v_exp_f32_e32 v199, v199
	v_exp_f32_e32 v200, v200
	v_mov_b32_e32 v192, v198
	v_fma_f32 v193, v193, v199, v200
	v_mul_f32_e32 v168, v168, v199
	v_mul_f32_e32 v169, v169, v199
	v_mul_f32_e32 v170, v170, v199
	v_mul_f32_e32 v171, v171, v199
	v_mul_f32_e32 v172, v172, v199
	v_mul_f32_e32 v173, v173, v199
	v_mul_f32_e32 v174, v174, v199
	v_mul_f32_e32 v175, v175, v199
	v_fmac_f32_e32 v168, v200, v104
	v_fmac_f32_e32 v169, v200, v105
	v_fmac_f32_e32 v170, v200, v106
	v_fmac_f32_e32 v171, v200, v107
	v_fmac_f32_e32 v172, v200, v108
	v_fmac_f32_e32 v173, v200, v109
	v_fmac_f32_e32 v174, v200, v110
	v_fmac_f32_e32 v175, v200, v111
	v_add_f32_e32 v194, v194, v196
	v_add_u32_e32 v195, s42, v195
	global_load_dwordx4 v[96:99], v195, s[20:21]
	global_load_dwordx4 v[100:103], v195, s[20:21] offset:256
	global_load_dwordx4 v[104:107], v195, s[24:25]
	global_load_dwordx4 v[108:111], v195, s[24:25] offset:256
	s_waitcnt vmcnt(28)
	v_fma_f32 v197, v160, v112, v194
	v_fmac_f32_e32 v197, v161, v113
	v_fmac_f32_e32 v197, v162, v114
	v_fmac_f32_e32 v197, v163, v115
	v_fmac_f32_e32 v197, v164, v116
	v_fmac_f32_e32 v197, v165, v117
	v_fmac_f32_e32 v197, v166, v118
	v_fmac_f32_e32 v197, v167, v119
	s_nop 1
	v_add_f32_dpp v197, v197, v197 row_ror:8 row_mask:0xf bank_mask:0xf
	s_nop 1
	v_add_f32_dpp v197, v197, v197 row_ror:4 row_mask:0xf bank_mask:0xf
	s_nop 1
	v_add_f32_dpp v197, v197, v197 row_ror:2 row_mask:0xf bank_mask:0xf
	s_nop 1
	v_add_f32_dpp v197, v197, v197 row_ror:1 row_mask:0xf bank_mask:0xf
	v_max_f32_e32 v198, v192, v197
	v_sub_f32_e32 v199, v192, v198
	v_sub_f32_e32 v200, v197, v198
	v_exp_f32_e32 v199, v199
	v_exp_f32_e32 v200, v200
	v_mov_b32_e32 v192, v198
	v_fma_f32 v193, v193, v199, v200
	v_mul_f32_e32 v168, v168, v199
	v_mul_f32_e32 v169, v169, v199
	v_mul_f32_e32 v170, v170, v199
	v_mul_f32_e32 v171, v171, v199
	v_mul_f32_e32 v172, v172, v199
	v_mul_f32_e32 v173, v173, v199
	v_mul_f32_e32 v174, v174, v199
	v_mul_f32_e32 v175, v175, v199
	v_fmac_f32_e32 v168, v200, v120
	v_fmac_f32_e32 v169, v200, v121
	v_fmac_f32_e32 v170, v200, v122
	v_fmac_f32_e32 v171, v200, v123
	v_fmac_f32_e32 v172, v200, v124
	v_fmac_f32_e32 v173, v200, v125
	v_fmac_f32_e32 v174, v200, v126
	v_fmac_f32_e32 v175, v200, v127
	v_add_f32_e32 v194, v194, v196
	v_add_u32_e32 v195, s42, v195
	global_load_dwordx4 v[112:115], v195, s[20:21]
	global_load_dwordx4 v[116:119], v195, s[20:21] offset:256
	global_load_dwordx4 v[120:123], v195, s[24:25]
	global_load_dwordx4 v[124:127], v195, s[24:25] offset:256
	s_add_u32 s33, s33, 1
	s_cmp_lt_u32 s33, 11
	s_cbranch_scc1 .Las_tripR2
	s_branch .Las_last
.Las_tripA:
	s_cmp_eq_u32 s33, 3
	s_cbranch_scc0 .Las_sw1A
	v_mov_b32_e32 v195, v176
	s_mov_b32 s42, 0xffff0000
	s_cmp_eq_u32 s43, 1
	s_cbranch_scc0 .Las_sw1A
	s_mov_b32 s42, 0xfffc0000
.Las_sw1A:
	s_cmp_eq_u32 s33, 7
	s_cbranch_scc0 .Las_sw2A
	v_mov_b32_e32 v195, v177
	s_mov_b32 s42, 0xfffc0000
	s_cmp_eq_u32 s43, 1
	s_cbranch_scc0 .Las_sw2A
	s_mov_b32 s42, 0xffff0000

; __device__ __forceinline__ float fexp2(float x) { return __builtin_amdgcn_exp2f(x); }
; __device__ __forceinline__ void attn_sample_item(const P& p, int wi, int lane) {
;     ...
;         for (int jj = 0; jj < 33; ++jj) {
;             const int j = 4 * jj + kg; const bool valid = j <= 128; const int jc = valid ? j : 128;
;             const int idx = 2048 + i - d * jc;
;             f32x4 k0, k1, v0, v1;
;             if (idx < 2048) { const size_t off = (((size_t)bs * 2048 + idx) * 8 + h) * 128 + 8 * li;
;                 k0 = __builtin_nontemporal_load((const f32x4*)(p.cache_k + off)); k1 = __builtin_nontemporal_load((const f32x4*)(p.cache_k + off + 4)); v0 = __builtin_nontemporal_load((const f32x4*)(p.cache_v + off)); v1 = __builtin_nontemporal_load((const f32x4*)(p.cache_v + off + 4)); }
;             else { const int nr = bs * 4 + (idx - 2048); const float rsn = rstd1[TP + nr]; const int c0 = 4096 + h * 128 + 8 * li;
;                 k0 = acc1_4(ACC1, nr, c0) * rsn; k1 = acc1_4(ACC1, nr, c0 + 4) * rsn; v0 = acc1_4(ACC1, nr, c0 + 1024) * rsn; v1 = acc1_4(ACC1, nr, c0 + 1028) * rsn; }
;             float dot = (q[0] * k0[0] + q[1] * k0[1]) + (q[2] * k0[2] + q[3] * k0[3]) + (q[4] * k1[0] + q[5] * k1[1]) + (q[6] * k1[2] + q[7] * k1[3]);
;             dot += __shfl_xor(dot, 1); dot += __shfl_xor(dot, 2); dot += __shfl_xor(dot, 4); dot += __shfl_xor(dot, 8);
;             const float s = valid ? dot - sl * (float)(d * j) : -INFINITY;
;             const float mn = fmaxf(m, s), sc = fexp2(m - mn), pe = fexp2(s - mn);
;             l = l * sc + pe;
;             acc[0] = acc[0] * sc + pe * v0[0]; acc[1] = acc[1] * sc + pe * v0[1]; acc[2] = acc[2] * sc + pe * v0[2]; acc[3] = acc[3] * sc + pe * v0[3];
;             acc[4] = acc[4] * sc + pe * v1[0]; acc[5] = acc[5] * sc + pe * v1[1]; acc[6] = acc[6] * sc + pe * v1[2]; acc[7] = acc[7] * sc + pe * v1[3];
;             m = mn;
;         }
.Las_last:
	s_waitcnt vmcnt(28)
	v_fma_f32 v197, v160, v0, v194
	v_fmac_f32_e32 v197, v161, v1
	v_fmac_f32_e32 v197, v162, v2
	v_fmac_f32_e32 v197, v163, v3
	v_fmac_f32_e32 v197, v164, v4
	v_fmac_f32_e32 v197, v165, v5
	v_fmac_f32_e32 v197, v166, v6
	v_fmac_f32_e32 v197, v167, v7
	s_nop 1
	v_add_f32_dpp v197, v197, v197 row_ror:8 row_mask:0xf bank_mask:0xf
	s_nop 1
	v_add_f32_dpp v197, v197, v197 row_ror:4 row_mask:0xf bank_mask:0xf
	s_nop 1
	v_add_f32_dpp v197, v197, v197 row_ror:2 row_mask:0xf bank_mask:0xf
	s_nop 1
	v_add_f32_dpp v197, v197, v197 row_ror:1 row_mask:0xf bank_mask:0xf
	v_max_f32_e32 v198, v192, v197
	v_sub_f32_e32 v199, v192, v198
	v_sub_f32_e32 v200, v197, v198
	v_exp_f32_e32 v199, v199
	v_exp_f32_e32 v200, v200
	v_mov_b32_e32 v192, v198
	v_fma_f32 v193, v193, v199, v200
	v_mul_f32_e32 v168, v168, v199
	v_mul_f32_e32 v169, v169, v199
	v_mul_f32_e32 v170, v170, v199
	v_mul_f32_e32 v171, v171, v199
	v_mul_f32_e32 v172, v172, v199
	v_mul_f32_e32 v173, v173, v199
	v_mul_f32_e32 v174, v174, v199
	v_mul_f32_e32 v175, v175, v199
	v_fmac_f32_e32 v168, v200, v8
	v_fmac_f32_e32 v169, v200, v9
	v_fmac_f32_e32 v170, v200, v10
	v_fmac_f32_e32 v171, v200, v11
	v_fmac_f32_e32 v172, v200, v12
	v_fmac_f32_e32 v173, v200, v13
	v_fmac_f32_e32 v174, v200, v14
	v_fmac_f32_e32 v175, v200, v15
	v_add_f32_e32 v194, v194, v196
	s_waitcnt vmcnt(24)
	v_fma_f32 v197, v160, v16, v194
	v_fmac_f32_e32 v197, v161, v17
	v_fmac_f32_e32 v197, v162, v18
	v_fmac_f32_e32 v197, v163, v19
	v_fmac_f32_e32 v197, v164, v20
	v_fmac_f32_e32 v197, v165, v21
	v_fmac_f32_e32 v197, v166, v22
	v_fmac_f32_e32 v197, v167, v23
	s_nop 1
	v_add_f32_dpp v197, v197, v197 row_ror:8 row_mask:0xf bank_mask:0xf
	s_nop 1
	v_add_f32_dpp v197, v197, v197 row_ror:4 row_mask:0xf bank_mask:0xf
	s_nop 1
	v_add_f32_dpp v197, v197, v197 row_ror:2 row_mask:0xf bank_mask:0xf
	s_nop 1
	v_add_f32_dpp v197, v197, v197 row_ror:1 row_mask:0xf bank_mask:0xf
	v_max_f32_e32 v198, v192, v197
	v_sub_f32_e32 v199, v192, v198
	v_sub_f32_e32 v200, v197, v198
	v_exp_f32_e32 v199, v199
	v_exp_f32_e32 v200, v200
	v_mov_b32_e32 v192, v198
	v_fma_f32 v193, v193, v199, v200
	v_mul_f32_e32 v168, v168, v199
	v_mul_f32_e32 v169, v169, v199
	v_mul_f32_e32 v170, v170, v199
	v_mul_f32_e32 v171, v171, v199
	v_mul_f32_e32 v172, v172, v199
	v_mul_f32_e32 v173, v173, v199
	v_mul_f32_e32 v174, v174, v199
	v_mul_f32_e32 v175, v175, v199
	v_fmac_f32_e32 v168, v200, v24
	v_fmac_f32_e32 v169, v200, v25
	v_fmac_f32_e32 v170, v200, v26
	v_fmac_f32_e32 v171, v200, v27
	v_fmac_f32_e32 v172, v200, v28
	v_fmac_f32_e32 v173, v200, v29
	v_fmac_f32_e32 v174, v200, v30
	v_fmac_f32_e32 v175, v200, v31
	v_add_f32_e32 v194, v194, v196
	s_waitcnt vmcnt(20)
	v_fma_f32 v197, v160, v32, v194
	v_fmac_f32_e32 v197, v161, v33
	v_fmac_f32_e32 v197, v162, v34
	v_fmac_f32_e32 v197, v163, v35
	v_fmac_f32_e32 v197, v164, v36
	v_fmac_f32_e32 v197, v165, v37
	v_fmac_f32_e32 v197, v166, v38
	v_fmac_f32_e32 v197, v167, v39
	s_nop 1
	v_add_f32_dpp v197, v197, v197 row_ror:8 row_mask:0xf bank_mask:0xf
	s_nop 1
	v_add_f32_dpp v197, v197, v197 row_ror:4 row_mask:0xf bank_mask:0xf
	s_nop 1
	v_add_f32_dpp v197, v197, v197 row_ror:2 row_mask:0xf bank_mask:0xf
	s_nop 1
	v_add_f32_dpp v197, v197, v197 row_ror:1 row_mask:0xf bank_mask:0xf
	v_max_f32_e32 v198, v192, v197
	v_sub_f32_e32 v199, v192, v198
	v_sub_f32_e32 v200, v197, v198
	v_exp_f32_e32 v199, v199
	v_exp_f32_e32 v200, v200
	v_mov_b32_e32 v192, v198
	v_fma_f32 v193, v193, v199, v200
	v_mul_f32_e32 v168, v168, v199
	v_mul_f32_e32 v169, v169, v199
	v_mul_f32_e32 v170, v170, v199
	v_mul_f32_e32 v171, v171, v199
	v_mul_f32_e32 v172, v172, v199
	v_mul_f32_e32 v173, v173, v199
	v_mul_f32_e32 v174, v174, v199
	v_mul_f32_e32 v175, v175, v199
	v_fmac_f32_e32 v168, v200, v40
	v_fmac_f32_e32 v169, v200, v41
	v_fmac_f32_e32 v170, v200, v42
	v_fmac_f32_e32 v171, v200, v43
	v_fmac_f32_e32 v172, v200, v44
	v_fmac_f32_e32 v173, v200, v45
	v_fmac_f32_e32 v174, v200, v46
	v_fmac_f32_e32 v175, v200, v47
	v_add_f32_e32 v194, v194, v196
	s_waitcnt vmcnt(16)
	v_fma_f32 v197, v160, v48, v194
	v_fmac_f32_e32 v197, v161, v49
	v_fmac_f32_e32 v197, v162, v50
	v_fmac_f32_e32 v197, v163, v51
	v_fmac_f32_e32 v197, v164, v52
	v_fmac_f32_e32 v197, v165, v53
	v_fmac_f32_e32 v197, v166, v54
	v_fmac_f32_e32 v197, v167, v55
	s_nop 1
	v_add_f32_dpp v197, v197, v197 row_ror:8 row_mask:0xf bank_mask:0xf
	s_nop 1
	v_add_f32_dpp v197, v197, v197 row_ror:4 row_mask:0xf bank_mask:0xf
	s_nop 1
	v_add_f32_dpp v197, v197, v197 row_ror:2 row_mask:0xf bank_mask:0xf
	s_nop 1
	v_add_f32_dpp v197, v197, v197 row_ror:1 row_mask:0xf bank_mask:0xf
	v_max_f32_e32 v198, v192, v197
	v_sub_f32_e32 v199, v192, v198
	v_sub_f32_e32 v200, v197, v198
	v_exp_f32_e32 v199, v199
	v_exp_f32_e32 v200, v200
	v_mov_b32_e32 v192, v198
	v_fma_f32 v193, v193, v199, v200
	v_mul_f32_e32 v168, v168, v199
	v_mul_f32_e32 v169, v169, v199
	v_mul_f32_e32 v170, v170, v199
	v_mul_f32_e32 v171, v171, v199
	v_mul_f32_e32 v172, v172, v199
	v_mul_f32_e32 v173, v173, v199
	v_mul_f32_e32 v174, v174, v199
	v_mul_f32_e32 v175, v175, v199
	v_fmac_f32_e32 v168, v200, v56
	v_fmac_f32_e32 v169, v200, v57
	v_fmac_f32_e32 v170, v200, v58
	v_fmac_f32_e32 v171, v200, v59
	v_fmac_f32_e32 v172, v200, v60
	v_fmac_f32_e32 v173, v200, v61
	v_fmac_f32_e32 v174, v200, v62
	v_fmac_f32_e32 v175, v200, v63
	v_add_f32_e32 v194, v194, v196
	s_waitcnt vmcnt(12)
; __device__ __forceinline__ float fexp2(float x) { return __builtin_amdgcn_exp2f(x); }
; __device__ __forceinline__ void attn_sample_item(const P& p, int wi, int lane) {
;     ...
;         for (int jj = 0; jj < 33; ++jj) {
;             const int j = 4 * jj + kg; const bool valid = j <= 128; const int jc = valid ? j : 128;
;             const int idx = 2048 + i - d * jc;
;             f32x4 k0, k1, v0, v1;
;             if (idx < 2048) { const size_t off = (((size_t)bs * 2048 + idx) * 8 + h) * 128 + 8 * li;
;                 k0 = __builtin_nontemporal_load((const f32x4*)(p.cache_k + off)); k1 = __builtin_nontemporal_load((const f32x4*)(p.cache_k + off + 4)); v0 = __builtin_nontemporal_load((const f32x4*)(p.cache_v + off)); v1 = __builtin_nontemporal_load((const f32x4*)(p.cache_v + off + 4)); }
;             else { const int nr = bs * 4 + (idx - 2048); const float rsn = rstd1[TP + nr]; const int c0 = 4096 + h * 128 + 8 * li;
;                 k0 = acc1_4(ACC1, nr, c0) * rsn; k1 = acc1_4(ACC1, nr, c0 + 4) * rsn; v0 = acc1_4(ACC1, nr, c0 + 1024) * rsn; v1 = acc1_4(ACC1, nr, c0 + 1028) * rsn; }
;             float dot = (q[0] * k0[0] + q[1] * k0[1]) + (q[2] * k0[2] + q[3] * k0[3]) + (q[4] * k1[0] + q[5] * k1[1]) + (q[6] * k1[2] + q[7] * k1[3]);
;             dot += __shfl_xor(dot, 1); dot += __shfl_xor(dot, 2); dot += __shfl_xor(dot, 4); dot += __shfl_xor(dot, 8);
;             const float s = valid ? dot - sl * (float)(d * j) : -INFINITY;
;             const float mn = fmaxf(m, s), sc = fexp2(m - mn), pe = fexp2(s - mn);
;             l = l * sc + pe;
;             acc[0] = acc[0] * sc + pe * v0[0]; acc[1] = acc[1] * sc + pe * v0[1]; acc[2] = acc[2] * sc + pe * v0[2]; acc[3] = acc[3] * sc + pe * v0[3];
;             acc[4] = acc[4] * sc + pe * v1[0]; acc[5] = acc[5] * sc + pe * v1[1]; acc[6] = acc[6] * sc + pe * v1[2]; acc[7] = acc[7] * sc + pe * v1[3];
;             m = mn;
;         }
	v_fma_f32 v197, v160, v64, v194
	v_fmac_f32_e32 v197, v161, v65
	v_fmac_f32_e32 v197, v162, v66
	v_fmac_f32_e32 v197, v163, v67
	v_fmac_f32_e32 v197, v164, v68
	v_fmac_f32_e32 v197, v165, v69
	v_fmac_f32_e32 v197, v166, v70
	v_fmac_f32_e32 v197, v167, v71
	s_nop 1
	v_add_f32_dpp v197, v197, v197 row_ror:8 row_mask:0xf bank_mask:0xf
	s_nop 1
	v_add_f32_dpp v197, v197, v197 row_ror:4 row_mask:0xf bank_mask:0xf
	s_nop 1
	v_add_f32_dpp v197, v197, v197 row_ror:2 row_mask:0xf bank_mask:0xf
	s_nop 1
	v_add_f32_dpp v197, v197, v197 row_ror:1 row_mask:0xf bank_mask:0xf
	v_max_f32_e32 v198, v192, v197
	v_sub_f32_e32 v199, v192, v198
	v_sub_f32_e32 v200, v197, v198
	v_exp_f32_e32 v199, v199
	v_exp_f32_e32 v200, v200
	v_mov_b32_e32 v192, v198
	v_fma_f32 v193, v193, v199, v200
	v_mul_f32_e32 v168, v168, v199
	v_mul_f32_e32 v169, v169, v199
	v_mul_f32_e32 v170, v170, v199
	v_mul_f32_e32 v171, v171, v199
	v_mul_f32_e32 v172, v172, v199
	v_mul_f32_e32 v173, v173, v199
	v_mul_f32_e32 v174, v174, v199
	v_mul_f32_e32 v175, v175, v199
	v_fmac_f32_e32 v168, v200, v72
	v_fmac_f32_e32 v169, v200, v73
	v_fmac_f32_e32 v170, v200, v74
	v_fmac_f32_e32 v171, v200, v75
	v_fmac_f32_e32 v172, v200, v76
	v_fmac_f32_e32 v173, v200, v77
	v_fmac_f32_e32 v174, v200, v78
	v_fmac_f32_e32 v175, v200, v79
	v_add_f32_e32 v194, v194, v196
	s_waitcnt vmcnt(8)
	v_fma_f32 v197, v160, v80, v194
	v_fmac_f32_e32 v197, v161, v81
	v_fmac_f32_e32 v197, v162, v82
	v_fmac_f32_e32 v197, v163, v83
	v_fmac_f32_e32 v197, v164, v84
	v_fmac_f32_e32 v197, v165, v85
	v_fmac_f32_e32 v197, v166, v86
	v_fmac_f32_e32 v197, v167, v87
	s_nop 1
	v_add_f32_dpp v197, v197, v197 row_ror:8 row_mask:0xf bank_mask:0xf
	s_nop 1
	v_add_f32_dpp v197, v197, v197 row_ror:4 row_mask:0xf bank_mask:0xf
	s_nop 1
	v_add_f32_dpp v197, v197, v197 row_ror:2 row_mask:0xf bank_mask:0xf
	s_nop 1
	v_add_f32_dpp v197, v197, v197 row_ror:1 row_mask:0xf bank_mask:0xf
	v_max_f32_e32 v198, v192, v197
	v_sub_f32_e32 v199, v192, v198
	v_sub_f32_e32 v200, v197, v198
	v_exp_f32_e32 v199, v199
	v_exp_f32_e32 v200, v200
	v_mov_b32_e32 v192, v198
	v_fma_f32 v193, v193, v199, v200
	v_mul_f32_e32 v168, v168, v199
	v_mul_f32_e32 v169, v169, v199
	v_mul_f32_e32 v170, v170, v199
	v_mul_f32_e32 v171, v171, v199
	v_mul_f32_e32 v172, v172, v199
	v_mul_f32_e32 v173, v173, v199
	v_mul_f32_e32 v174, v174, v199
	v_mul_f32_e32 v175, v175, v199
	v_fmac_f32_e32 v168, v200, v88
	v_fmac_f32_e32 v169, v200, v89
	v_fmac_f32_e32 v170, v200, v90
	v_fmac_f32_e32 v171, v200, v91
	v_fmac_f32_e32 v172, v200, v92
	v_fmac_f32_e32 v173, v200, v93
	v_fmac_f32_e32 v174, v200, v94
	v_fmac_f32_e32 v175, v200, v95
	v_add_f32_e32 v194, v194, v196
	s_waitcnt vmcnt(4)
	v_fma_f32 v197, v160, v96, v194
	v_fmac_f32_e32 v197, v161, v97
	v_fmac_f32_e32 v197, v162, v98
	v_fmac_f32_e32 v197, v163, v99
	v_fmac_f32_e32 v197, v164, v100
	v_fmac_f32_e32 v197, v165, v101
	v_fmac_f32_e32 v197, v166, v102
	v_fmac_f32_e32 v197, v167, v103
	s_nop 1
	v_add_f32_dpp v197, v197, v197 row_ror:8 row_mask:0xf bank_mask:0xf
	s_nop 1
	v_add_f32_dpp v197, v197, v197 row_ror:4 row_mask:0xf bank_mask:0xf
	s_nop 1
	v_add_f32_dpp v197, v197, v197 row_ror:2 row_mask:0xf bank_mask:0xf
	s_nop 1
	v_add_f32_dpp v197, v197, v197 row_ror:1 row_mask:0xf bank_mask:0xf
	v_max_f32_e32 v198, v192, v197
	v_sub_f32_e32 v199, v192, v198
	v_sub_f32_e32 v200, v197, v198
	v_exp_f32_e32 v199, v199
	v_exp_f32_e32 v200, v200
	v_mov_b32_e32 v192, v198
	v_fma_f32 v193, v193, v199, v200
	v_mul_f32_e32 v168, v168, v199
	v_mul_f32_e32 v169, v169, v199
	v_mul_f32_e32 v170, v170, v199
	v_mul_f32_e32 v171, v171, v199
	v_mul_f32_e32 v172, v172, v199
	v_mul_f32_e32 v173, v173, v199
	v_mul_f32_e32 v174, v174, v199
	v_mul_f32_e32 v175, v175, v199
	v_fmac_f32_e32 v168, v200, v104
	v_fmac_f32_e32 v169, v200, v105
	v_fmac_f32_e32 v170, v200, v106
	v_fmac_f32_e32 v171, v200, v107
	v_fmac_f32_e32 v172, v200, v108
	v_fmac_f32_e32 v173, v200, v109
	v_fmac_f32_e32 v174, v200, v110
	v_fmac_f32_e32 v175, v200, v111
	v_add_f32_e32 v194, v194, v196
	s_waitcnt vmcnt(0)
	s_cmp_eq_u32 s43, 2
	s_cbranch_scc0 .Las_nomask
	v_mov_b32_e32 v182, 0xff800000
	v_cmp_eq_u32_e32 vcc, 0, v183
	s_nop 1
	v_cndmask_b32_e32 v194, v182, v194, vcc
; __device__ __forceinline__ float fexp2(float x) { return __builtin_amdgcn_exp2f(x); }
; __device__ __forceinline__ void attn_sample_item(const P& p, int wi, int lane) {
;     ...
;             float dot = (q[0] * k0[0] + q[1] * k0[1]) + (q[2] * k0[2] + q[3] * k0[3]) + (q[4] * k1[0] + q[5] * k1[1]) + (q[6] * k1[2] + q[7] * k1[3]);
;             dot += __shfl_xor(dot, 1); dot += __shfl_xor(dot, 2); dot += __shfl_xor(dot, 4); dot += __shfl_xor(dot, 8);
;             const float s = valid ? dot - sl * (float)(d * j) : -INFINITY;
;             const float mn = fmaxf(m, s), sc = fexp2(m - mn), pe = fexp2(s - mn);
;             l = l * sc + pe;
;             acc[0] = acc[0] * sc + pe * v0[0]; acc[1] = acc[1] * sc + pe * v0[1]; acc[2] = acc[2] * sc + pe * v0[2]; acc[3] = acc[3] * sc + pe * v0[3];
;             acc[4] = acc[4] * sc + pe * v1[0]; acc[5] = acc[5] * sc + pe * v1[1]; acc[6] = acc[6] * sc + pe * v1[2]; acc[7] = acc[7] * sc + pe * v1[3];
;             m = mn;
;         }
;     }
;     float mt = fmaxf(m, __shfl_xor(m, 16)); mt = fmaxf(mt, __shfl_xor(mt, 32));
;     const float f = fexp2(m - mt);
;     l *= f; l += __shfl_xor(l, 16); l += __shfl_xor(l, 32);
;     const float inv = 1.f / l;
;     float* o = (float*)(ws + O_ATTS) + (size_t)srow * 1024 + h * 128 + 8 * li;
; #pragma unroll
;     for (int e = 0; e < 8; ++e) { float a = acc[e] * f; a += __shfl_xor(a, 16); a += __shfl_xor(a, 32); acc[e] = a * inv; }
;     if (kg == 0) { *(f32x4*)o = (f32x4){acc[0], acc[1], acc[2], acc[3]}; *(f32x4*)(o + 4) = (f32x4){acc[4], acc[5], acc[6], acc[7]}; }
.Las_nomask:
	v_fma_f32 v197, v160, v112, v194
	v_fmac_f32_e32 v197, v161, v113
	v_fmac_f32_e32 v197, v162, v114
	v_fmac_f32_e32 v197, v163, v115
	v_fmac_f32_e32 v197, v164, v116
	v_fmac_f32_e32 v197, v165, v117
	v_fmac_f32_e32 v197, v166, v118
	v_fmac_f32_e32 v197, v167, v119
	s_nop 1
	v_add_f32_dpp v197, v197, v197 row_ror:8 row_mask:0xf bank_mask:0xf
	s_nop 1
	v_add_f32_dpp v197, v197, v197 row_ror:4 row_mask:0xf bank_mask:0xf
	s_nop 1
	v_add_f32_dpp v197, v197, v197 row_ror:2 row_mask:0xf bank_mask:0xf
	s_nop 1
	v_add_f32_dpp v197, v197, v197 row_ror:1 row_mask:0xf bank_mask:0xf
	v_max_f32_e32 v198, v192, v197
	v_sub_f32_e32 v199, v192, v198
	v_sub_f32_e32 v200, v197, v198
	v_exp_f32_e32 v199, v199
	v_exp_f32_e32 v200, v200
	v_mov_b32_e32 v192, v198
	v_fma_f32 v193, v193, v199, v200
	v_mul_f32_e32 v168, v168, v199
	v_mul_f32_e32 v169, v169, v199
	v_mul_f32_e32 v170, v170, v199
	v_mul_f32_e32 v171, v171, v199
	v_mul_f32_e32 v172, v172, v199
	v_mul_f32_e32 v173, v173, v199
	v_mul_f32_e32 v174, v174, v199
	v_mul_f32_e32 v175, v175, v199
	v_fmac_f32_e32 v168, v200, v120
	v_fmac_f32_e32 v169, v200, v121
	v_fmac_f32_e32 v170, v200, v122
	v_fmac_f32_e32 v171, v200, v123
	v_fmac_f32_e32 v172, v200, v124
	v_fmac_f32_e32 v173, v200, v125
	v_fmac_f32_e32 v174, v200, v126
	v_fmac_f32_e32 v175, v200, v127
	v_and_b32_e32 v182, 63, v230
	v_xor_b32_e32 v183, 16, v182
	v_lshlrev_b32_e32 v183, 2, v183
	v_xor_b32_e32 v182, 32, v182
	v_lshlrev_b32_e32 v182, 2, v182
	ds_bpermute_b32 v197, v183, v192
	s_waitcnt lgkmcnt(0)
	v_max_f32_e32 v198, v192, v197
	ds_bpermute_b32 v197, v182, v198
	s_waitcnt lgkmcnt(0)
	v_max_f32_e32 v198, v198, v197
	v_sub_f32_e32 v199, v192, v198
	v_exp_f32_e32 v199, v199
	s_nop 0
	v_mul_f32_e32 v193, v193, v199
	v_mul_f32_e32 v168, v168, v199
	v_mul_f32_e32 v169, v169, v199
	v_mul_f32_e32 v170, v170, v199
	v_mul_f32_e32 v171, v171, v199
	v_mul_f32_e32 v172, v172, v199
	v_mul_f32_e32 v173, v173, v199
	v_mul_f32_e32 v174, v174, v199
	v_mul_f32_e32 v175, v175, v199
	ds_bpermute_b32 v0, v183, v193
	ds_bpermute_b32 v1, v183, v168
	ds_bpermute_b32 v2, v183, v169
	ds_bpermute_b32 v3, v183, v170
	ds_bpermute_b32 v4, v183, v171
	ds_bpermute_b32 v5, v183, v172
	ds_bpermute_b32 v6, v183, v173
	ds_bpermute_b32 v7, v183, v174
	ds_bpermute_b32 v8, v183, v175
	s_waitcnt lgkmcnt(0)
	v_add_f32_e32 v193, v193, v0
	v_add_f32_e32 v168, v168, v1
	v_add_f32_e32 v169, v169, v2
	v_add_f32_e32 v170, v170, v3
	v_add_f32_e32 v171, v171, v4
	v_add_f32_e32 v172, v172, v5
	v_add_f32_e32 v173, v173, v6
	v_add_f32_e32 v174, v174, v7
	v_add_f32_e32 v175, v175, v8
	ds_bpermute_b32 v0, v182, v193
	ds_bpermute_b32 v1, v182, v168
	ds_bpermute_b32 v2, v182, v169
	ds_bpermute_b32 v3, v182, v170
	ds_bpermute_b32 v4, v182, v171
	ds_bpermute_b32 v5, v182, v172
	ds_bpermute_b32 v6, v182, v173
	ds_bpermute_b32 v7, v182, v174
	ds_bpermute_b32 v8, v182, v175
	s_waitcnt lgkmcnt(0)
	v_add_f32_e32 v193, v193, v0
	v_add_f32_e32 v168, v168, v1
	v_add_f32_e32 v169, v169, v2
	v_add_f32_e32 v170, v170, v3
	v_add_f32_e32 v171, v171, v4
	v_add_f32_e32 v172, v172, v5
	v_add_f32_e32 v173, v173, v6
	v_add_f32_e32 v174, v174, v7
	v_add_f32_e32 v175, v175, v8
	v_rcp_f32_e32 v197, v193
	s_nop 0
	v_fma_f32 v198, -v193, v197, 1.0
	v_fma_f32 v197, v198, v197, v197
	v_mul_f32_e32 v168, v168, v197
	v_mul_f32_e32 v169, v169, v197
	v_mul_f32_e32 v170, v170, v197
	v_mul_f32_e32 v171, v171, v197
	v_mul_f32_e32 v172, v172, v197
	v_mul_f32_e32 v173, v173, v197
	v_mul_f32_e32 v174, v174, v197
	v_mul_f32_e32 v175, v175, v197
	v_and_b32_e32 v182, 15, v230
	v_lshlrev_b32_e32 v182, 4, v182
	s_lshl_b32 s43, s17, 12
	s_add_u32 s43, s43, s23
	v_add_u32_e32 v182, s43, v182
	s_mov_b64 exec, 0xffff
	global_store_dwordx4 v182, v[168:171], s[30:31]
	global_store_dwordx4 v182, v[172:175], s[30:31] offset:256
	s_mov_b64 exec, -1
	s_add_i32 s3, s3, s77
	s_cmpk_gt_i32 s3, 0x3ff
	s_cbranch_scc0 .Las_item
